# row-norm butterfly shuffles (xor 1/2/4/8 within 16 lanes) in the q/k/v and retention epilogues: ds_bpermute replaced by DPP moves
# speedup vs baseline: 1.0080x; 1.0027x over previous
.LBB0_178:
	s_andn2_b64 vcc, exec, s[0:1]
	s_mov_b64 s[0:1], 0x1000
	s_cbranch_vccnz .LBB0_189
	s_cmp_lg_u32 s77, 0
	s_cbranch_scc0 .LBB0_195
	s_cmp_lg_u32 s77, 1
	s_cselect_b64 s[72:73], -1, 0
	s_lshl_b32 s0, s76, 9
	s_add_u32 s4, s82, s0
	s_addc_u32 s5, s83, 0
	s_cmp_eq_u32 s77, 2
	s_cselect_b64 s[70:71], -1, 0
	s_and_b64 s[0:1], s[70:71], exec
	s_cselect_b32 s1, s57, s59
	s_cselect_b32 s0, s56, s58
	s_cmp_eq_u32 s77, 1
	s_cselect_b32 s0, s4, s0
	s_cselect_b32 s1, s5, s1
	global_load_dword v98, v190, s[0:1]
	global_load_dword v116, v190, s[0:1] offset:320
	global_load_dword v120, v190, s[0:1] offset:384
	global_load_dword v102, v190, s[0:1] offset:64
	global_load_dword v106, v190, s[0:1] offset:128
	v_and_b32_e32 v65, 64, v199
	global_load_dword v110, v190, s[0:1] offset:192
	v_xor_b32_e32 v64, 1, v199
	v_add_u32_e32 v65, 64, v65
	global_load_dword v112, v190, s[0:1] offset:256
	global_load_dword v124, v190, s[0:1] offset:448
	v_cmp_lt_i32_e32 vcc, v64, v65
	v_mul_f32_e32 v66, v4, v4
	v_mul_f32_e32 v67, v5, v5
	v_mul_f32_e32 v70, v36, v36
	v_mul_f32_e32 v71, v37, v37
	v_cndmask_b32_e32 v64, v199, v64, vcc
	v_fma_f32 v66, v0, v0, v66
	v_fma_f32 v67, v1, v1, v67
	v_lshlrev_b32_e32 v99, 2, v64
	v_xor_b32_e32 v64, 2, v199
	v_fma_f32 v66, v8, v8, v66
	v_fma_f32 v67, v9, v9, v67
	v_cmp_lt_i32_e32 vcc, v64, v65
	v_fma_f32 v66, v12, v12, v66
	v_fma_f32 v67, v13, v13, v67
	v_fma_f32 v70, v32, v32, v70
	v_fma_f32 v71, v33, v33, v71
	v_cndmask_b32_e32 v64, v199, v64, vcc
	v_fma_f32 v66, v16, v16, v66
	v_fma_f32 v67, v17, v17, v67
	v_lshlrev_b32_e32 v103, 2, v64
	v_xor_b32_e32 v64, 4, v199
	v_fma_f32 v66, v20, v20, v66
	v_fma_f32 v67, v21, v21, v67
	v_cmp_lt_i32_e32 vcc, v64, v65
	v_fma_f32 v66, v24, v24, v66
	v_fma_f32 v67, v25, v25, v67
	v_fma_f32 v70, v40, v40, v70
	v_fma_f32 v71, v41, v41, v71
	v_cndmask_b32_e32 v64, v199, v64, vcc
	v_fma_f32 v66, v28, v28, v66
	v_fma_f32 v67, v29, v29, v67
	v_lshlrev_b32_e32 v107, 2, v64
	v_xor_b32_e32 v64, 8, v199
	v_mov_b32_dpp v72, v66 quad_perm:[1,0,3,2] row_mask:0xf bank_mask:0xf
	v_mov_b32_dpp v73, v67 quad_perm:[1,0,3,2] row_mask:0xf bank_mask:0xf
	v_cmp_lt_i32_e32 vcc, v64, v65
	v_fma_f32 v70, v44, v44, v70
	v_fma_f32 v71, v45, v45, v71
	v_mul_f32_e32 v68, v38, v38
	v_mul_f32_e32 v69, v39, v39
	v_cndmask_b32_e32 v64, v199, v64, vcc
	v_lshlrev_b32_e32 v111, 2, v64
	v_mul_f32_e32 v64, v6, v6
	v_mul_f32_e32 v65, v7, v7
	s_waitcnt lgkmcnt(0)
	v_add_f32_e32 v66, v66, v72
	v_add_f32_e32 v67, v67, v73
	v_fma_f32 v64, v2, v2, v64
	v_fma_f32 v65, v3, v3, v65
	v_mov_b32_dpp v72, v66 quad_perm:[2,3,0,1] row_mask:0xf bank_mask:0xf
	v_fma_f32 v64, v10, v10, v64
	v_fma_f32 v65, v11, v11, v65
	v_mov_b32_dpp v73, v67 quad_perm:[2,3,0,1] row_mask:0xf bank_mask:0xf
	v_fma_f32 v64, v14, v14, v64
	v_fma_f32 v65, v15, v15, v65
	v_fma_f32 v70, v48, v48, v70
	v_fma_f32 v71, v49, v49, v71
	v_fma_f32 v64, v18, v18, v64
	v_fma_f32 v65, v19, v19, v65
	v_fma_f32 v70, v52, v52, v70
	v_fma_f32 v71, v53, v53, v71
	v_fma_f32 v64, v22, v22, v64
	v_fma_f32 v65, v23, v23, v65
	s_waitcnt lgkmcnt(0)
	v_add_f32_e32 v66, v66, v72
	v_add_f32_e32 v67, v67, v73
	v_fma_f32 v64, v26, v26, v64
	v_fma_f32 v65, v27, v27, v65
	v_fma_f32 v80, v56, v56, v70
	v_fma_f32 v81, v57, v57, v71
	v_fma_f32 v64, v30, v30, v64
	v_fma_f32 v65, v31, v31, v65
	s_nop 0
	v_mov_b32_dpp v74, v64 quad_perm:[1,0,3,2] row_mask:0xf bank_mask:0xf
	s_nop 0
	v_mov_b32_dpp v75, v65 quad_perm:[1,0,3,2] row_mask:0xf bank_mask:0xf
	v_mov_b32_dpp v72, v66 row_half_mirror row_mask:0xf bank_mask:0xf
	v_mov_b32_dpp v73, v67 row_half_mirror row_mask:0xf bank_mask:0xf
	v_fma_f32 v84, v60, v60, v80
	v_fma_f32 v85, v61, v61, v81
	v_fma_f32 v68, v34, v34, v68
	v_fma_f32 v69, v35, v35, v69
	v_mov_b32_dpp v86, v84 quad_perm:[1,0,3,2] row_mask:0xf bank_mask:0xf
	v_mov_b32_dpp v87, v85 quad_perm:[1,0,3,2] row_mask:0xf bank_mask:0xf
	v_fma_f32 v68, v42, v42, v68
	v_fma_f32 v69, v43, v43, v69
	s_waitcnt lgkmcnt(0)
	v_add_f32_e32 v64, v64, v74
	v_add_f32_e32 v65, v65, v75
	v_fma_f32 v68, v46, v46, v68
	v_fma_f32 v69, v47, v47, v69
	v_add_f32_e32 v66, v66, v72
	v_add_f32_e32 v67, v67, v73
	v_fma_f32 v68, v50, v50, v68
	v_fma_f32 v69, v51, v51, v69
	v_mov_b32_dpp v72, v64 quad_perm:[2,3,0,1] row_mask:0xf bank_mask:0xf
	v_fma_f32 v68, v54, v54, v68
	v_fma_f32 v69, v55, v55, v69
	v_mov_b32_dpp v73, v65 quad_perm:[2,3,0,1] row_mask:0xf bank_mask:0xf
	v_fma_f32 v96, v58, v58, v68
	v_fma_f32 v97, v59, v59, v69
	v_mov_b32_dpp v68, v66 row_mirror row_mask:0xf bank_mask:0xf
	v_mov_b32_dpp v69, v67 row_mirror row_mask:0xf bank_mask:0xf
	v_add_f32_e32 v90, v84, v86
	v_add_f32_e32 v91, v85, v87
	s_nop 0
	v_mov_b32_dpp v100, v90 quad_perm:[2,3,0,1] row_mask:0xf bank_mask:0xf
	s_nop 0
	v_mov_b32_dpp v101, v91 quad_perm:[2,3,0,1] row_mask:0xf bank_mask:0xf
	s_waitcnt lgkmcnt(0)
	v_add_f32_e32 v64, v64, v72
	v_add_f32_e32 v65, v65, v73
	v_add_f32_e32 v66, v66, v68
	v_add_f32_e32 v67, v67, v69
	v_mov_b32_dpp v68, v64 row_half_mirror row_mask:0xf bank_mask:0xf
	v_mov_b32_dpp v69, v65 row_half_mirror row_mask:0xf bank_mask:0xf
	v_add_f32_e32 v100, v90, v100
	v_add_f32_e32 v101, v91, v101
	s_nop 0
	v_mov_b32_dpp v108, v100 row_half_mirror row_mask:0xf bank_mask:0xf
	s_nop 0
	v_mov_b32_dpp v109, v101 row_half_mirror row_mask:0xf bank_mask:0xf
	v_mov_b64_e32 v[104:105], s[46:47]
	s_waitcnt lgkmcnt(0)
	v_add_f32_e32 v64, v64, v68
	v_add_f32_e32 v65, v65, v69
	s_nop 0
	v_mov_b32_dpp v68, v64 row_mirror row_mask:0xf bank_mask:0xf
	s_nop 0
	v_mov_b32_dpp v69, v65 row_mirror row_mask:0xf bank_mask:0xf
	v_add_f32_e32 v100, v100, v108
	v_add_f32_e32 v101, v101, v109
	s_nop 0
	v_mov_b32_dpp v108, v100 row_mirror row_mask:0xf bank_mask:0xf
	s_nop 0
	v_mov_b32_dpp v109, v101 row_mirror row_mask:0xf bank_mask:0xf
	v_fma_f32 v66, v66, s38, v104
	v_fma_f32 v67, v67, s38, v104
	s_waitcnt lgkmcnt(0)
	v_add_f32_e32 v64, v64, v68
	v_add_f32_e32 v65, v65, v69
	v_mul_f32_e32 v70, 0x4b800000, v66
	v_cmp_gt_f32_e32 vcc, s47, v66
	v_fma_f32 v64, v64, s38, v104
	v_fma_f32 v65, v65, s38, v104
	v_fma_f32 v96, v62, v62, v96
	v_fma_f32 v97, v63, v63, v97
	v_cndmask_b32_e32 v66, v66, v70, vcc
	v_mul_f32_e32 v70, 0x4b800000, v67
	v_cmp_gt_f32_e64 s[0:1], s47, v67
	v_mul_f32_e32 v68, 0x4b800000, v64
	v_cmp_gt_f32_e64 s[4:5], s47, v64
	v_add_f32_e32 v100, v100, v108
	v_add_f32_e32 v101, v101, v109
	v_mov_b32_dpp v108, v96 quad_perm:[1,0,3,2] row_mask:0xf bank_mask:0xf
	v_mov_b32_dpp v109, v97 quad_perm:[1,0,3,2] row_mask:0xf bank_mask:0xf
	v_cndmask_b32_e64 v67, v67, v70, s[0:1]
	v_cndmask_b32_e64 v64, v64, v68, s[4:5]
	v_mul_f32_e32 v68, 0x4b800000, v65
	v_cmp_gt_f32_e64 s[6:7], s47, v65
	v_rsq_f32_e32 v66, v66
	v_rsq_f32_e32 v67, v67
	v_cndmask_b32_e64 v65, v65, v68, s[6:7]
	v_rsq_f32_e32 v64, v64
	v_rsq_f32_e32 v65, v65
	s_waitcnt lgkmcnt(0)
	v_add_f32_e32 v96, v96, v108
	v_add_f32_e32 v97, v97, v109
	v_mul_f32_e32 v68, s52, v66
	v_mul_f32_e32 v69, s52, v67
	v_mov_b32_dpp v108, v96 quad_perm:[2,3,0,1] row_mask:0xf bank_mask:0xf
	v_mov_b32_dpp v109, v97 quad_perm:[2,3,0,1] row_mask:0xf bank_mask:0xf
	v_cndmask_b32_e64 v93, v67, v69, s[0:1]
	v_cndmask_b32_e32 v92, v66, v68, vcc
	v_mul_f32_e32 v66, s52, v64
	v_mul_f32_e32 v67, s52, v65
	v_fma_f32 v100, v100, s38, v104
	v_fma_f32 v101, v101, s38, v104
	v_cndmask_b32_e64 v95, v65, v67, s[6:7]
	v_cndmask_b32_e64 v94, v64, v66, s[4:5]
	s_waitcnt vmcnt(0)
	v_mul_f32_e32 v64, v94, v98
	v_mul_f32_e32 v65, v95, v98
	v_mul_f32_e32 v68, v92, v98
	v_mul_f32_e32 v69, v93, v98
	v_mul_f32_e32 v99, 0x4b800000, v100
	v_cmp_gt_f32_e32 vcc, s47, v100
	v_cmp_gt_f32_e64 s[0:1], s47, v101
	s_waitcnt lgkmcnt(0)
	v_add_f32_e32 v96, v96, v108
	v_add_f32_e32 v97, v97, v109
	v_cndmask_b32_e32 v99, v100, v99, vcc
	v_rsq_f32_e32 v100, v99
	v_mul_f32_e32 v99, 0x4b800000, v101
	v_cndmask_b32_e64 v99, v101, v99, s[0:1]
	v_mov_b32_dpp v108, v96 row_half_mirror row_mask:0xf bank_mask:0xf
	v_mov_b32_dpp v109, v97 row_half_mirror row_mask:0xf bank_mask:0xf
	v_rsq_f32_e32 v101, v99
	v_mul_f32_e32 v88, v94, v116
	v_mul_f32_e32 v89, v95, v116
	v_mul_f32_e32 v114, v92, v120
	v_mul_f32_e32 v115, v93, v120
	v_mul_f32_e32 v86, v22, v88
	v_mul_f32_e32 v87, v23, v89
	v_mul_f32_e32 v88, v94, v120
	v_mul_f32_e32 v89, v95, v120
	s_waitcnt lgkmcnt(0)
	v_add_f32_e32 v108, v96, v108
	v_add_f32_e32 v109, v97, v109
	v_mul_f32_e32 v90, v26, v88
	v_mul_f32_e32 v91, v27, v89
	v_mul_f32_e32 v88, v24, v114
	v_mul_f32_e32 v89, v25, v115
	v_mul_f32_e32 v114, s52, v100
	v_mul_f32_e32 v115, s52, v101
	v_mul_f32_e32 v66, v2, v64
	v_mul_f32_e32 v67, v3, v65
	v_cndmask_b32_e64 v127, v101, v115, s[0:1]
	v_cndmask_b32_e32 v126, v100, v114, vcc
	v_mov_b32_dpp v114, v108 row_mirror row_mask:0xf bank_mask:0xf
	v_mov_b32_dpp v115, v109 row_mirror row_mask:0xf bank_mask:0xf
	v_mul_f32_e32 v100, v126, v98
	v_mul_f32_e32 v101, v127, v98
	v_mul_f32_e32 v64, v0, v68
	v_mul_f32_e32 v65, v1, v69
	v_mul_f32_e32 v68, v94, v102
	v_mul_f32_e32 v69, v95, v102
	v_mul_f32_e32 v72, v92, v102
	v_mul_f32_e32 v73, v93, v102
	s_waitcnt lgkmcnt(0)
	v_add_f32_e32 v108, v108, v114
	v_add_f32_e32 v109, v109, v115
	v_mul_f32_e32 v118, v126, v106
	v_mul_f32_e32 v119, v127, v106
	v_fma_f32 v105, v109, s38, v104
	v_fma_f32 v104, v108, s38, v104
	v_mul_f32_e32 v70, v6, v68
	v_mul_f32_e32 v71, v7, v69
	v_mul_f32_e32 v99, 0x4b800000, v104
	v_cmp_gt_f32_e32 vcc, s47, v104
	v_cmp_gt_f32_e64 s[0:1], s47, v105
	v_mul_f32_e32 v68, v4, v72
	v_mul_f32_e32 v69, v5, v73
	v_cndmask_b32_e32 v99, v104, v99, vcc
	v_rsq_f32_e32 v114, v99
	v_mul_f32_e32 v99, 0x4b800000, v105
	v_cndmask_b32_e64 v99, v105, v99, s[0:1]
	v_rsq_f32_e32 v115, v99
	v_mul_f32_e32 v72, v94, v106
	v_mul_f32_e32 v73, v95, v106
	v_mul_f32_e32 v76, v92, v106
	v_mul_f32_e32 v77, v93, v106
	v_mul_f32_e32 v104, v40, v118
	v_mul_f32_e32 v105, v41, v119
	v_mul_f32_e32 v118, s52, v114
	v_mul_f32_e32 v119, s52, v115
	v_mul_f32_e32 v74, v10, v72
	v_mul_f32_e32 v75, v11, v73
	v_mul_f32_e32 v72, v8, v76
	v_mul_f32_e32 v73, v9, v77
	v_mul_f32_e32 v76, v94, v110
	v_mul_f32_e32 v77, v95, v110
	v_mul_f32_e32 v82, v92, v110
	v_mul_f32_e32 v83, v93, v110
	v_cndmask_b32_e64 v201, v115, v119, s[0:1]
	v_cndmask_b32_e32 v200, v114, v118, vcc
	v_mul_f32_e32 v78, v14, v76
	v_mul_f32_e32 v79, v15, v77
	v_mul_f32_e32 v76, v12, v82
	v_mul_f32_e32 v77, v13, v83
	v_mul_f32_e32 v82, v94, v112
	v_mul_f32_e32 v83, v95, v112
	v_mul_f32_e32 v80, v92, v112
	v_mul_f32_e32 v81, v93, v112
	v_mul_f32_e32 v84, v92, v116
	v_mul_f32_e32 v85, v93, v116
	v_mul_f32_e32 v94, v94, v124
	v_mul_f32_e32 v95, v95, v124
	v_mul_f32_e32 v92, v92, v124
	v_mul_f32_e32 v93, v93, v124
	v_mul_f32_e32 v96, v32, v100
	v_mul_f32_e32 v97, v33, v101
	v_mul_f32_e32 v100, v126, v102
	v_mul_f32_e32 v101, v127, v102
	v_mul_f32_e32 v108, v126, v110
	v_mul_f32_e32 v109, v127, v110
	v_mul_f32_e32 v99, v98, v201
	v_mul_f32_e32 v98, v98, v200
	v_mul_f32_e32 v103, v102, v201
	v_mul_f32_e32 v102, v102, v200
	v_mul_f32_e32 v107, v106, v201
	v_mul_f32_e32 v106, v106, v200
	v_mul_f32_e32 v111, v110, v201
	v_mul_f32_e32 v110, v110, v200
	v_mul_f32_e32 v114, v200, v112
	v_mul_f32_e32 v115, v201, v112
	v_mul_f32_e32 v113, v127, v112
	v_mul_f32_e32 v112, v126, v112
	v_mul_f32_e32 v118, v200, v116
	v_mul_f32_e32 v119, v201, v116
	v_mul_f32_e32 v117, v127, v116
	v_mul_f32_e32 v116, v126, v116
	v_mul_f32_e32 v122, v200, v120
	v_mul_f32_e32 v123, v201, v120
	v_mul_f32_e32 v121, v127, v120
	v_mul_f32_e32 v120, v126, v120
	v_mul_f32_e32 v200, v200, v124
	v_mul_f32_e32 v201, v201, v124
	v_mul_f32_e32 v125, v127, v124
	v_mul_f32_e32 v124, v126, v124
	s_cmp_lg_u32 s77, 2
	v_mul_f32_e32 v82, v18, v82
	v_mul_f32_e32 v83, v19, v83
	v_mul_f32_e32 v80, v16, v80
	v_mul_f32_e32 v81, v17, v81
	v_mul_f32_e32 v84, v20, v84
	v_mul_f32_e32 v85, v21, v85
	v_mul_f32_e32 v94, v30, v94
	v_mul_f32_e32 v95, v31, v95
	v_mul_f32_e32 v92, v28, v92
	v_mul_f32_e32 v93, v29, v93
	v_mul_f32_e32 v100, v36, v100
	v_mul_f32_e32 v101, v37, v101
	v_mul_f32_e32 v108, v44, v108
	v_mul_f32_e32 v109, v45, v109
	v_mul_f32_e32 v98, v34, v98
	v_mul_f32_e32 v99, v35, v99
	v_mul_f32_e32 v102, v38, v102
	v_mul_f32_e32 v103, v39, v103
	v_mul_f32_e32 v106, v42, v106
	v_mul_f32_e32 v107, v43, v107
	v_mul_f32_e32 v110, v46, v110
	v_mul_f32_e32 v111, v47, v111
	v_mul_f32_e32 v114, v50, v114
	v_mul_f32_e32 v115, v51, v115
	v_mul_f32_e32 v112, v48, v112
	v_mul_f32_e32 v113, v49, v113
	v_mul_f32_e32 v118, v54, v118
	v_mul_f32_e32 v119, v55, v119
	v_mul_f32_e32 v116, v52, v116
	v_mul_f32_e32 v117, v53, v117
	v_mul_f32_e32 v122, v58, v122
	v_mul_f32_e32 v123, v59, v123
	v_mul_f32_e32 v120, v56, v120
	v_mul_f32_e32 v121, v57, v121
	v_mul_f32_e32 v126, v62, v200
	v_mul_f32_e32 v127, v63, v201
	v_mul_f32_e32 v124, v60, v124
	v_mul_f32_e32 v125, v61, v125
	s_cbranch_scc1 .LBB0_182
	v_mul_f32_e32 v66, s60, v66
	v_mul_f32_e32 v67, s60, v67
	v_mul_f32_e32 v64, s60, v64
	v_mul_f32_e32 v65, s60, v65
	v_mul_f32_e32 v70, s60, v70
	v_mul_f32_e32 v71, s60, v71
	v_mul_f32_e32 v68, s60, v68
	v_mul_f32_e32 v69, s60, v69
	v_mul_f32_e32 v74, s60, v74
	v_mul_f32_e32 v75, s60, v75
	v_mul_f32_e32 v72, s60, v72
	v_mul_f32_e32 v73, s60, v73
	v_mul_f32_e32 v78, s60, v78
	v_mul_f32_e32 v79, s60, v79
	v_mul_f32_e32 v76, s60, v76
	v_mul_f32_e32 v77, s60, v77
	v_mul_f32_e32 v82, s60, v82
	v_mul_f32_e32 v83, s60, v83
	v_mul_f32_e32 v80, s60, v80
	v_mul_f32_e32 v81, s60, v81
	v_mul_f32_e32 v86, s60, v86
	v_mul_f32_e32 v87, s60, v87
	v_mul_f32_e32 v84, s60, v84
	v_mul_f32_e32 v85, s60, v85
	v_mul_f32_e32 v90, s60, v90
	v_mul_f32_e32 v91, s60, v91
	v_mul_f32_e32 v88, s60, v88
	v_mul_f32_e32 v89, s60, v89
	v_mul_f32_e32 v94, s60, v94
	v_mul_f32_e32 v95, s60, v95
	v_mul_f32_e32 v92, s60, v92
	v_mul_f32_e32 v93, s60, v93
	v_mul_f32_e32 v98, s60, v98
	v_mul_f32_e32 v99, s60, v99
	v_mul_f32_e32 v96, s60, v96
	v_mul_f32_e32 v97, s60, v97
	v_mul_f32_e32 v102, s60, v102
	v_mul_f32_e32 v103, s60, v103
	v_mul_f32_e32 v100, s60, v100
	v_mul_f32_e32 v101, s60, v101
	v_mul_f32_e32 v106, s60, v106
	v_mul_f32_e32 v107, s60, v107
	v_mul_f32_e32 v104, s60, v104
	v_mul_f32_e32 v105, s60, v105
	v_mul_f32_e32 v110, s60, v110
	v_mul_f32_e32 v111, s60, v111
	v_mul_f32_e32 v108, s60, v108
	v_mul_f32_e32 v109, s60, v109
	v_mul_f32_e32 v114, s60, v114
	v_mul_f32_e32 v115, s60, v115
	v_mul_f32_e32 v112, s60, v112
	v_mul_f32_e32 v113, s60, v113
	v_mul_f32_e32 v118, s60, v118
	v_mul_f32_e32 v119, s60, v119
	v_mul_f32_e32 v116, s60, v116
	v_mul_f32_e32 v117, s60, v117
	v_mul_f32_e32 v122, s60, v122
	v_mul_f32_e32 v123, s60, v123
	v_mul_f32_e32 v120, s60, v120
	v_mul_f32_e32 v121, s60, v121
	v_mul_f32_e32 v126, s60, v126
	v_mul_f32_e32 v127, s60, v127
	v_mul_f32_e32 v124, s60, v124
	v_mul_f32_e32 v125, s60, v125

.LBB0_437:
	s_andn2_b64 vcc, exec, s[4:5]
	s_mov_b64 s[4:5], 0x1000
	s_cbranch_vccnz .LBB0_443
	s_cmp_lg_u32 s65, 0
	s_cbranch_scc0 .LBB0_447
	s_lshl_b64 s[58:59], s[0:1], 13
	s_cmp_eq_u32 s65, 1
	s_cselect_b64 s[56:57], -1, 0
	s_and_b64 s[0:1], s[56:57], exec
	s_cselect_b32 s1, s43, s45
	s_cselect_b32 s0, s42, s44
	v_mov_b32_e32 v120, v18
	v_mov_b32_e32 v121, v22
	v_mul_f32_e32 v122, v120, v120
	v_mul_f32_e32 v123, v121, v121
	global_load_dword v143, v192, s[0:1]
	global_load_dword v141, v192, s[0:1] offset:64
	global_load_dword v125, v192, s[0:1] offset:128
	global_load_dword v121, v192, s[0:1] offset:192
	global_load_dword v142, v192, s[0:1] offset:256
	global_load_dword v140, v192, s[0:1] offset:320
	v_and_b32_e32 v77, 64, v201
	v_xor_b32_e32 v76, 1, v201
	v_add_u32_e32 v77, 64, v77
	v_cmp_lt_i32_e32 vcc, v76, v77
	v_mov_b32_e32 v82, v41
	v_mov_b32_e32 v83, v45
	v_cndmask_b32_e32 v76, v201, v76, vcc
	v_lshlrev_b32_e32 v146, 2, v76
	v_xor_b32_e32 v76, 2, v201
	v_cmp_lt_i32_e32 vcc, v76, v77
	v_mul_f32_e32 v82, v82, v82
	v_mul_f32_e32 v83, v83, v83
	v_mul_f32_e32 v86, v36, v36
	v_mul_f32_e32 v87, v37, v37
	v_cndmask_b32_e32 v76, v201, v76, vcc
	v_lshlrev_b32_e32 v147, 2, v76
	v_xor_b32_e32 v76, 4, v201
	v_cmp_lt_i32_e32 vcc, v76, v77
	v_mov_b32_e32 v78, v48
	v_mov_b32_e32 v79, v52
	v_cndmask_b32_e32 v76, v201, v76, vcc
	v_lshlrev_b32_e32 v148, 2, v76
	v_xor_b32_e32 v76, 8, v201
	v_cmp_lt_i32_e32 vcc, v76, v77
	v_mov_b32_e32 v77, v44
	v_fma_f32 v86, v32, v32, v86
	v_fma_f32 v87, v33, v33, v87
	v_cndmask_b32_e32 v76, v201, v76, vcc
	v_lshlrev_b32_e32 v149, 2, v76
	v_mov_b32_e32 v76, v40
	v_mul_f32_e32 v76, v76, v76
	v_mul_f32_e32 v77, v77, v77
	v_mov_b32_e32 v88, v49
	v_mov_b32_e32 v89, v53
	v_mov_b32_e32 v126, v82
	v_mov_b32_e32 v127, v76
	v_mul_f32_e32 v78, v78, v78
	v_mul_f32_e32 v79, v79, v79
	v_mul_f32_e32 v88, v88, v88
	v_mul_f32_e32 v89, v89, v89
	v_pk_add_f32 v[86:87], v[86:87], v[126:127] op_sel:[1,0] op_sel_hi:[0,1]
	v_mov_b32_e32 v76, v83
	v_mov_b32_e32 v80, v56
	v_mov_b32_e32 v81, v60
	v_mov_b32_e32 v90, v57
	v_mov_b32_e32 v91, v61
	v_add_f32_e32 v76, v86, v76
	v_add_f32_e32 v77, v87, v77
	v_mov_b32_e32 v82, v88
	v_mov_b32_e32 v83, v78
	v_mul_f32_e32 v80, v80, v80
	v_mul_f32_e32 v81, v81, v81
	v_mul_f32_e32 v90, v90, v90
	v_mul_f32_e32 v91, v91, v91
	v_add_f32_e32 v76, v76, v82
	v_add_f32_e32 v77, v77, v83
	v_mov_b32_e32 v78, v89
	v_add_f32_e32 v76, v76, v78
	v_add_f32_e32 v77, v77, v79
	v_mov_b32_e32 v78, v90
	v_mov_b32_e32 v79, v80
	v_add_f32_e32 v76, v76, v78
	v_add_f32_e32 v77, v77, v79
	v_mov_b32_e32 v80, v91
	v_add_f32_e32 v76, v76, v80
	v_add_f32_e32 v77, v77, v81
	s_nop 1
	v_mov_b32_dpp v79, v77 quad_perm:[1,0,3,2] row_mask:0xf bank_mask:0xf
	v_mov_b32_dpp v78, v76 quad_perm:[1,0,3,2] row_mask:0xf bank_mask:0xf
	global_load_dword v124, v192, s[0:1] offset:384
	global_load_dword v120, v192, s[0:1] offset:448
	v_mov_b32_e32 v88, v3
	v_mov_b32_e32 v89, v11
	s_waitcnt lgkmcnt(0)
	v_add_f32_e32 v76, v76, v78
	v_add_f32_e32 v77, v77, v79
	s_nop 1
	v_mov_b32_dpp v79, v77 quad_perm:[2,3,0,1] row_mask:0xf bank_mask:0xf
	v_mov_b32_dpp v78, v76 quad_perm:[2,3,0,1] row_mask:0xf bank_mask:0xf
	v_mov_b32_e32 v92, v42
	v_mov_b32_e32 v93, v46
	v_mov_b32_e32 v98, v43
	v_mov_b32_e32 v99, v47
	s_waitcnt lgkmcnt(0)
	v_add_f32_e32 v76, v76, v78
	v_add_f32_e32 v77, v77, v79
	s_nop 1
	v_mov_b32_dpp v79, v77 row_half_mirror row_mask:0xf bank_mask:0xf
	v_mov_b32_dpp v78, v76 row_half_mirror row_mask:0xf bank_mask:0xf
	v_mul_f32_e32 v90, v88, v88
	v_mul_f32_e32 v91, v89, v89
	v_mov_b32_e32 v88, v27
	v_mov_b32_e32 v89, v31
	v_mul_f32_e32 v84, v38, v38
	v_mul_f32_e32 v85, v39, v39
	s_waitcnt lgkmcnt(0)
	v_add_f32_e32 v76, v76, v78
	v_add_f32_e32 v77, v77, v79
	s_nop 1
	v_mov_b32_dpp v79, v77 row_mirror row_mask:0xf bank_mask:0xf
	v_mov_b32_dpp v78, v76 row_mirror row_mask:0xf bank_mask:0xf
	v_mul_f32_e32 v92, v92, v92
	v_mul_f32_e32 v93, v93, v93
	v_mul_f32_e32 v98, v98, v98
	v_mul_f32_e32 v99, v99, v99
	v_fma_f32 v84, v34, v34, v84
	v_fma_f32 v85, v35, v35, v85
	v_mov_b32_e32 v94, v50
	s_waitcnt lgkmcnt(0)
	v_add_f32_e32 v76, v76, v78
	v_add_f32_e32 v77, v77, v79
	v_mov_b64_e32 v[78:79], s[52:53]
	v_fma_f32 v76, v76, s46, v78
	v_fma_f32 v77, v77, s46, v78
	v_mov_b32_e32 v95, v54
	v_mul_f32_e32 v126, 0x4b800000, v77
	v_cmp_gt_f32_e32 vcc, s60, v77
	v_cmp_gt_f32_e64 s[0:1], s60, v76
	v_mov_b32_e32 v100, v51
	v_cndmask_b32_e32 v77, v77, v126, vcc
	v_rsq_f32_e32 v126, v77
	v_mul_f32_e32 v77, 0x4b800000, v76
	v_cndmask_b32_e64 v76, v76, v77, s[0:1]
	v_rsq_f32_e32 v127, v76
	v_mul_f32_e32 v76, v88, v88
	v_mul_f32_e32 v77, v89, v89
	v_mul_f32_e32 v88, 0x45800000, v126
	v_mov_b32_e32 v101, v55
	v_cndmask_b32_e32 v126, v126, v88, vcc
	v_mov_b32_e32 v88, v98
	v_mov_b32_e32 v89, v92
	v_mul_f32_e32 v94, v94, v94
	v_mul_f32_e32 v95, v95, v95
	v_mul_f32_e32 v100, v100, v100
	v_mul_f32_e32 v101, v101, v101
	v_pk_add_f32 v[84:85], v[84:85], v[88:89] op_sel:[1,0] op_sel_hi:[0,1]
	v_mov_b32_e32 v92, v99
	v_mov_b32_e32 v96, v58
	v_mov_b32_e32 v97, v62
	v_mov_b32_e32 v102, v59
	v_mov_b32_e32 v103, v63
	v_add_f32_e32 v84, v84, v92
	v_add_f32_e32 v85, v85, v93
	v_mov_b32_e32 v88, v100
	v_mov_b32_e32 v89, v94
	v_mul_f32_e32 v96, v96, v96
	v_mul_f32_e32 v97, v97, v97
	v_mul_f32_e32 v102, v102, v102
	v_mul_f32_e32 v103, v103, v103
	v_add_f32_e32 v84, v84, v88
	v_add_f32_e32 v85, v85, v89
	v_mov_b32_e32 v94, v101
	v_add_f32_e32 v84, v84, v94
	v_add_f32_e32 v85, v85, v95
	v_mov_b32_e32 v88, v102
	v_mov_b32_e32 v89, v96
	v_add_f32_e32 v84, v84, v88
	v_add_f32_e32 v85, v85, v89
	v_mov_b32_e32 v96, v103
	v_add_f32_e32 v84, v84, v96
	v_add_f32_e32 v85, v85, v97
	s_nop 1
	v_mov_b32_dpp v89, v85 quad_perm:[1,0,3,2] row_mask:0xf bank_mask:0xf
	v_mov_b32_dpp v88, v84 quad_perm:[1,0,3,2] row_mask:0xf bank_mask:0xf
	v_mul_f32_e32 v144, 0x45800000, v127
	v_mov_b32_e32 v104, v16
	v_mov_b32_e32 v105, v20
	v_mov_b32_e32 v110, v17
	s_waitcnt lgkmcnt(0)
	v_add_f32_e32 v84, v84, v88
	v_add_f32_e32 v85, v85, v89
	s_nop 1
	v_mov_b32_dpp v89, v85 quad_perm:[2,3,0,1] row_mask:0xf bank_mask:0xf
	v_mov_b32_dpp v88, v84 quad_perm:[2,3,0,1] row_mask:0xf bank_mask:0xf
	v_mov_b32_e32 v111, v21
	v_cndmask_b32_e64 v96, v127, v144, s[0:1]
	v_mul_f32_e32 v104, v104, v104
	v_mul_f32_e32 v105, v105, v105
	v_mul_f32_e32 v110, v110, v110
	v_mul_f32_e32 v111, v111, v111
	v_mul_f32_e32 v114, v12, v12
	v_mul_f32_e32 v115, v13, v13
	s_waitcnt vmcnt(0)
	v_mul_f32_e32 v92, v96, v143
	v_mov_b32_e32 v106, v0
	v_mov_b32_e32 v107, v8
	v_fma_f32 v114, v4, v4, v114
	v_fma_f32 v115, v5, v5, v115
	v_mov_b32_e32 v116, v1
	v_mov_b32_e32 v117, v9
	v_mul_f32_e32 v127, v33, v92
	s_waitcnt lgkmcnt(0)
	v_add_f32_e32 v84, v84, v88
	v_add_f32_e32 v85, v85, v89
	v_mov_b32_e32 v92, v110
	v_mov_b32_e32 v93, v104
	v_mul_f32_e32 v106, v106, v106
	v_mul_f32_e32 v107, v107, v107
	v_mul_f32_e32 v116, v116, v116
	v_mul_f32_e32 v117, v117, v117
	v_mov_b32_dpp v89, v85 row_half_mirror row_mask:0xf bank_mask:0xf
	v_mov_b32_dpp v88, v84 row_half_mirror row_mask:0xf bank_mask:0xf
	v_add_f32_e32 v92, v115, v92
	v_add_f32_e32 v93, v114, v93
	v_mov_b32_e32 v104, v111
	v_mov_b32_e32 v108, v24
	v_mov_b32_e32 v109, v28
	v_mov_b32_e32 v118, v25
	v_mov_b32_e32 v119, v29
	v_add_f32_e32 v92, v92, v104
	v_add_f32_e32 v93, v93, v105
	v_mov_b32_e32 v94, v116
	v_mov_b32_e32 v95, v106
	v_mul_f32_e32 v108, v108, v108
	v_mul_f32_e32 v109, v109, v109
	v_mul_f32_e32 v118, v118, v118
	v_mul_f32_e32 v119, v119, v119
	v_add_f32_e32 v92, v92, v94
	v_add_f32_e32 v93, v93, v95
	v_mov_b32_e32 v106, v117
	v_add_f32_e32 v92, v92, v106
	v_add_f32_e32 v93, v93, v107
	v_mov_b32_e32 v94, v118
	v_mov_b32_e32 v95, v108
	v_add_f32_e32 v92, v92, v94
	v_add_f32_e32 v93, v93, v95
	v_mov_b32_e32 v108, v119
	s_waitcnt lgkmcnt(0)
	v_add_f32_e32 v84, v84, v88
	v_add_f32_e32 v85, v85, v89
	v_add_f32_e32 v92, v92, v108
	v_add_f32_e32 v93, v93, v109
	v_mov_b32_dpp v89, v85 row_mirror row_mask:0xf bank_mask:0xf
	v_mov_b32_dpp v88, v84 row_mirror row_mask:0xf bank_mask:0xf
	v_mov_b32_dpp v95, v93 quad_perm:[1,0,3,2] row_mask:0xf bank_mask:0xf
	v_mov_b32_dpp v94, v92 quad_perm:[1,0,3,2] row_mask:0xf bank_mask:0xf
	v_mul_f32_e32 v33, v96, v141
	v_mul_f32_e32 v150, v37, v33
	s_waitcnt lgkmcnt(2)
	v_add_f32_e32 v84, v84, v88
	v_add_f32_e32 v85, v85, v89
	v_mul_f32_e32 v33, v96, v125
	s_waitcnt lgkmcnt(0)
	v_add_f32_e32 v88, v92, v94
	v_add_f32_e32 v89, v93, v95
	s_nop 1
	v_mov_b32_dpp v93, v89 quad_perm:[2,3,0,1] row_mask:0xf bank_mask:0xf
	v_mov_b32_dpp v92, v88 quad_perm:[2,3,0,1] row_mask:0xf bank_mask:0xf
	v_fma_f32 v84, v84, s46, v78
	v_fma_f32 v85, v85, s46, v78
	v_mul_f32_e32 v151, v41, v33
	v_mul_f32_e32 v37, 0x4b800000, v85
	v_cmp_gt_f32_e32 vcc, s60, v85
	s_waitcnt lgkmcnt(0)
	v_add_f32_e32 v88, v88, v92
	v_add_f32_e32 v89, v89, v93
	s_nop 1
	v_mov_b32_dpp v93, v89 row_half_mirror row_mask:0xf bank_mask:0xf
	v_mov_b32_dpp v92, v88 row_half_mirror row_mask:0xf bank_mask:0xf
	v_mul_f32_e32 v41, 0x4b800000, v84
	v_cmp_gt_f32_e64 s[0:1], s60, v84
	v_cndmask_b32_e32 v37, v85, v37, vcc
	v_mul_f32_e32 v33, v96, v121
	s_waitcnt lgkmcnt(0)
	v_add_f32_e32 v88, v88, v92
	v_add_f32_e32 v89, v89, v93
	s_nop 1
	v_mov_b32_dpp v93, v89 row_mirror row_mask:0xf bank_mask:0xf
	v_mov_b32_dpp v92, v88 row_mirror row_mask:0xf bank_mask:0xf
	v_cndmask_b32_e64 v41, v84, v41, s[0:1]
	v_mul_f32_e32 v203, v45, v33
	v_mul_f32_e32 v33, v96, v142
	v_rsq_f32_e32 v37, v37
	s_waitcnt lgkmcnt(0)
	v_add_f32_e32 v84, v88, v92
	v_add_f32_e32 v85, v89, v93
	v_mul_f32_e32 v204, v49, v33
	v_fma_f32 v84, v84, s46, v78
	v_fma_f32 v85, v85, s46, v78
	v_mul_f32_e32 v33, v96, v140
	v_mul_f32_e32 v45, 0x4b800000, v85
	v_cmp_gt_f32_e64 s[4:5], s60, v85
	v_rsq_f32_e32 v41, v41
	v_mul_f32_e32 v104, v53, v33
	v_cndmask_b32_e64 v45, v85, v45, s[4:5]
	v_mul_f32_e32 v33, v96, v124
	v_rsq_f32_e32 v45, v45
	v_mul_f32_e32 v105, v57, v33
	v_mul_f32_e32 v33, v96, v120
	v_mul_f32_e32 v106, v61, v33
	v_mul_f32_e32 v33, 0x45800000, v37
	v_cndmask_b32_e32 v92, v37, v33, vcc
	v_mul_f32_e32 v33, 0x45800000, v41
	v_cndmask_b32_e64 v88, v41, v33, s[0:1]
	v_mul_f32_e32 v33, 0x45800000, v45
	v_cndmask_b32_e64 v108, v45, v33, s[4:5]
	v_mul_f32_e32 v33, 0x4b800000, v84
	v_cmp_gt_f32_e32 vcc, s60, v84
	v_mov_b32_e32 v86, v19
	v_mov_b32_e32 v87, v23
	v_cndmask_b32_e32 v33, v84, v33, vcc
	v_lshl_add_u64 v[84:85], s[58:59], 0, v[72:73]
	v_lshlrev_b64 v[144:145], 2, v[84:85]
	v_lshl_add_u64 v[84:85], s[6:7], 0, v[144:145]
	v_lshl_add_u64 v[94:95], s[8:9], 0, v[144:145]
	global_load_dword v85, v[84:85], off
	s_nop 0
	global_load_dword v84, v[94:95], off
	v_or_b32_e32 v94, 64, v144
	v_mov_b32_e32 v95, v145
	v_lshl_add_u64 v[96:97], s[6:7], 0, v[94:95]
	v_lshl_add_u64 v[94:95], s[8:9], 0, v[94:95]
	global_load_dword v97, v[96:97], off
	s_nop 0
	global_load_dword v96, v[94:95], off
	v_or_b32_e32 v98, 0x80, v144
	v_mov_b32_e32 v99, v145
	v_lshl_add_u64 v[100:101], s[6:7], 0, v[98:99]
	v_lshl_add_u64 v[98:99], s[8:9], 0, v[98:99]
	global_load_dword v101, v[100:101], off
	s_nop 0
	global_load_dword v100, v[98:99], off
	v_or_b32_e32 v98, 0xc0, v144
	v_mov_b32_e32 v99, v145
	v_lshl_add_u64 v[102:103], s[6:7], 0, v[98:99]
	v_lshl_add_u64 v[98:99], s[8:9], 0, v[98:99]
	global_load_dword v103, v[102:103], off
	s_nop 0
	global_load_dword v102, v[98:99], off
	v_mul_f32_e32 v112, v14, v14
	v_mul_f32_e32 v113, v15, v15
	v_mul_f32_e32 v86, v86, v86
	v_mul_f32_e32 v87, v87, v87
	v_fma_f32 v112, v6, v6, v112
	v_fma_f32 v113, v7, v7, v113
	v_mov_b32_e32 v80, v2
	v_mov_b32_e32 v81, v10
	v_mov_b32_e32 v94, v86
	v_mov_b32_e32 v95, v122
	v_mul_f32_e32 v80, v80, v80
	v_mul_f32_e32 v81, v81, v81
	v_add_f32_e32 v94, v113, v94
	v_add_f32_e32 v95, v112, v95
	v_mov_b32_e32 v122, v87
	v_mov_b32_e32 v82, v26
	v_mov_b32_e32 v83, v30
	v_add_f32_e32 v86, v94, v122
	v_add_f32_e32 v87, v95, v123
	v_mov_b32_e32 v94, v90
	v_mov_b32_e32 v95, v80
	v_mul_f32_e32 v82, v82, v82
	v_mul_f32_e32 v83, v83, v83
	v_add_f32_e32 v86, v86, v94
	v_add_f32_e32 v87, v87, v95
	v_mov_b32_e32 v80, v91
	v_add_f32_e32 v80, v86, v80
	v_add_f32_e32 v81, v87, v81
	v_mov_b32_e32 v86, v76
	v_mov_b32_e32 v87, v82
	v_add_f32_e32 v80, v80, v86
	v_add_f32_e32 v81, v81, v87
	v_mov_b32_e32 v82, v77
	v_add_f32_e32 v76, v80, v82
	v_add_f32_e32 v77, v81, v83
	s_nop 1
	v_mov_b32_dpp v81, v77 quad_perm:[1,0,3,2] row_mask:0xf bank_mask:0xf
	v_mov_b32_dpp v80, v76 quad_perm:[1,0,3,2] row_mask:0xf bank_mask:0xf
	v_rsq_f32_e32 v33, v33
	v_mov_b32_e32 v49, v32
	v_mov_b32_e32 v53, v36
	v_mov_b32_e32 v57, v40
	s_waitcnt lgkmcnt(0)
	v_add_f32_e32 v76, v76, v80
	v_add_f32_e32 v77, v77, v81
	s_nop 1
	v_mov_b32_dpp v81, v77 quad_perm:[2,3,0,1] row_mask:0xf bank_mask:0xf
	v_mov_b32_dpp v80, v76 quad_perm:[2,3,0,1] row_mask:0xf bank_mask:0xf
	v_mul_f32_e32 v37, 0x45800000, v33
	v_cndmask_b32_e32 v33, v33, v37, vcc
	v_mul_f32_e32 v37, v33, v143
	v_mul_f32_e32 v41, v5, v37
	s_waitcnt lgkmcnt(0)
	v_add_f32_e32 v76, v76, v80
	v_add_f32_e32 v77, v77, v81
	s_nop 1
	v_mov_b32_dpp v81, v77 row_half_mirror row_mask:0xf bank_mask:0xf
	v_mov_b32_dpp v80, v76 row_half_mirror row_mask:0xf bank_mask:0xf
	v_mul_f32_e32 v5, v33, v141
	v_mul_f32_e32 v45, v13, v5
	v_mul_f32_e32 v5, v33, v125
	v_mul_f32_e32 v5, v17, v5
	s_waitcnt lgkmcnt(0)
	v_add_f32_e32 v76, v76, v80
	v_add_f32_e32 v77, v77, v81
	s_nop 1
	v_mov_b32_dpp v81, v77 row_mirror row_mask:0xf bank_mask:0xf
	v_mov_b32_dpp v80, v76 row_mirror row_mask:0xf bank_mask:0xf
	v_mul_f32_e32 v13, v33, v121
	v_mul_f32_e32 v17, v33, v142
	v_mul_f32_e32 v13, v21, v13
	v_mul_f32_e32 v21, v1, v17
	v_mul_f32_e32 v1, v33, v140
	s_waitcnt lgkmcnt(0)
	v_add_f32_e32 v76, v76, v80
	v_add_f32_e32 v77, v77, v81
	v_mul_f32_e32 v109, v9, v1
	v_mul_f32_e32 v1, v33, v124
	v_fma_f32 v76, v76, s46, v78
	v_fma_f32 v77, v77, s46, v78
	v_mul_f32_e32 v17, v25, v1
	v_mul_f32_e32 v9, 0x4b800000, v77
	v_cmp_gt_f32_e32 vcc, s60, v77
	v_mul_f32_e32 v25, 0x4b800000, v76
	v_cmp_gt_f32_e64 s[0:1], s60, v76
	v_cndmask_b32_e32 v9, v77, v9, vcc
	v_mul_f32_e32 v1, v33, v120
	v_cndmask_b32_e64 v25, v76, v25, s[0:1]
	v_mul_f32_e32 v76, v126, v142
	v_mul_f32_e32 v77, v126, v143
	v_mul_f32_e32 v32, v48, v76
	v_mul_f32_e32 v33, v49, v77
	s_waitcnt vmcnt(7)
	v_mov_b32_e32 v76, v85
	s_waitcnt vmcnt(6)
	v_mov_b32_e32 v77, v84
	v_rsq_f32_e32 v9, v9
	v_mul_f32_e32 v48, v32, v84
	v_mul_f32_e32 v49, v33, v85
	v_mul_f32_e32 v32, v32, v76
	v_mul_f32_e32 v33, v33, v77
	v_mul_f32_e32 v76, v126, v140
	v_mul_f32_e32 v77, v126, v141
	v_rsq_f32_e32 v25, v25
	v_mul_f32_e32 v36, v52, v76
	v_mul_f32_e32 v37, v53, v77
	s_waitcnt vmcnt(5)
	v_mov_b32_e32 v76, v97
	s_waitcnt vmcnt(4)
	v_mov_b32_e32 v77, v96
	v_mul_f32_e32 v52, v36, v96
	v_mul_f32_e32 v53, v37, v97
	v_mul_f32_e32 v36, v36, v76
	v_mul_f32_e32 v37, v37, v77
	v_mul_f32_e32 v76, v126, v124
	v_mul_f32_e32 v77, v126, v125
	v_mul_f32_e32 v56, v56, v76
	v_mul_f32_e32 v57, v57, v77
	s_waitcnt vmcnt(3)
	v_mov_b32_e32 v78, v101
	s_waitcnt vmcnt(2)
	v_mov_b32_e32 v79, v100
	v_mul_f32_e32 v110, v29, v1
	v_mul_f32_e32 v1, 0x45800000, v9
	v_mul_f32_e32 v76, v56, v100
	v_mul_f32_e32 v77, v57, v101
	v_mul_f32_e32 v56, v56, v78
	v_mul_f32_e32 v57, v57, v79
	v_mul_f32_e32 v78, v126, v120
	v_mul_f32_e32 v79, v126, v121
	v_mov_b32_e32 v61, v44
	v_cndmask_b32_e32 v148, v9, v1, vcc
	v_mul_f32_e32 v1, 0x45800000, v25
	v_mul_f32_e32 v60, v60, v78
	v_mul_f32_e32 v61, v61, v79
	v_cndmask_b32_e64 v146, v25, v1, s[0:1]
	s_waitcnt vmcnt(0)
	v_mul_f32_e32 v78, v60, v102
	v_mul_f32_e32 v79, v61, v103
	v_mov_b32_e32 v80, v103
	v_mov_b32_e32 v81, v102
	v_cndmask_b32_e64 v64, v202, 1.0, s[56:57]
	v_mul_f32_e32 v60, v60, v80
	v_mul_f32_e32 v61, v61, v81
	v_or_b32_e32 v80, 0x100, v144
	v_mov_b32_e32 v81, v145
	v_lshl_add_u64 v[82:83], s[6:7], 0, v[80:81]
	v_lshl_add_u64 v[80:81], s[8:9], 0, v[80:81]
	global_load_dword v1, v[82:83], off
	global_load_dword v9, v[80:81], off
	v_or_b32_e32 v80, 0x140, v144
	v_mov_b32_e32 v81, v145
	v_lshl_add_u64 v[82:83], s[6:7], 0, v[80:81]
	v_lshl_add_u64 v[80:81], s[8:9], 0, v[80:81]
	v_or_b32_e32 v84, 0x180, v144
	v_mov_b32_e32 v85, v145
	v_lshl_add_u64 v[86:87], s[6:7], 0, v[84:85]
	v_lshl_add_u64 v[84:85], s[8:9], 0, v[84:85]
	global_load_dword v25, v[82:83], off
	global_load_dword v29, v[80:81], off
	global_load_dword v40, v[86:87], off
	global_load_dword v44, v[84:85], off
	v_or_b32_e32 v80, 0x1c0, v144
	v_mov_b32_e32 v81, v145
	v_lshl_add_u64 v[82:83], s[6:7], 0, v[80:81]
	v_lshl_add_u64 v[80:81], s[8:9], 0, v[80:81]
	global_load_dword v89, v[82:83], off
	global_load_dword v93, v[80:81], off
	v_mov_b32_e32 v82, v33
	v_mov_b32_e32 v84, v37
	v_mov_b32_e32 v80, v49
	v_mov_b32_e32 v86, v53
	v_mov_b32_e32 v90, v77
	v_mov_b32_e32 v94, v57
	v_mov_b32_e32 v96, v79
	v_mov_b32_e32 v98, v61
	s_waitcnt vmcnt(7)
	v_mul_f32_e32 v33, v204, v1
	s_waitcnt vmcnt(6)
	v_mul_f32_e32 v83, v127, v9
	v_mul_f32_e32 v81, v127, v1
	v_mul_f32_e32 v49, v204, v9
	v_add_f32_e32 v32, v32, v82
	v_add_f32_e32 v33, v33, v83
	v_add_f32_e64 v48, v80, -v48
	v_add_f32_e64 v49, v81, -v49
	s_waitcnt vmcnt(5)
	v_mul_f32_e32 v37, v104, v25
	s_waitcnt vmcnt(4)
	v_mul_f32_e32 v85, v150, v29
	v_mul_f32_e32 v87, v150, v25
	v_mul_f32_e32 v53, v104, v29
	s_waitcnt vmcnt(3)
	v_mul_f32_e32 v91, v151, v40
	s_waitcnt vmcnt(2)
	v_mul_f32_e32 v77, v105, v44
	v_mul_f32_e32 v95, v151, v44
	v_mul_f32_e32 v57, v105, v40
	s_waitcnt vmcnt(1)
	v_mul_f32_e32 v97, v203, v89
	s_waitcnt vmcnt(0)
	v_mul_f32_e32 v79, v106, v93
	v_mul_f32_e32 v99, v203, v93
	v_mul_f32_e32 v61, v106, v89
	v_add_f32_e32 v36, v36, v84
	v_add_f32_e32 v37, v37, v85
	v_add_f32_e32 v56, v56, v94
	v_add_f32_e32 v57, v57, v95
	v_add_f32_e32 v60, v60, v98
	v_add_f32_e32 v61, v61, v99
	v_mul_f32_e32 v84, v64, v32
	v_mul_f32_e32 v85, v64, v33
	v_add_f32_e64 v32, v86, -v52
	v_add_f32_e64 v33, v87, -v53
	v_mul_f32_e32 v86, v64, v36
	v_mul_f32_e32 v87, v64, v37
	v_add_f32_e64 v36, v90, -v76
	v_add_f32_e64 v37, v91, -v77
	v_add_f32_e64 v52, v96, -v78
	v_add_f32_e64 v53, v97, -v79
	v_mul_f32_e32 v90, v64, v56
	v_mul_f32_e32 v91, v64, v57
	v_mul_f32_e32 v76, v64, v48
	v_mul_f32_e32 v77, v64, v49
	v_mul_f32_e32 v78, v64, v32
	v_mul_f32_e32 v79, v64, v33
	v_mul_f32_e32 v80, v64, v36
	v_mul_f32_e32 v81, v64, v37
	v_mul_f32_e32 v82, v64, v52
	v_mul_f32_e32 v83, v64, v53
	v_mul_f32_e32 v94, v64, v60
	v_mul_f32_e32 v95, v64, v61
	v_or_b32_e32 v32, 0x200, v144
	v_mov_b32_e32 v33, v145
	v_or_b32_e32 v48, 0x240, v144
	v_mov_b32_e32 v49, v145
	v_lshl_add_u64 v[36:37], s[6:7], 0, v[32:33]
	v_lshl_add_u64 v[32:33], s[8:9], 0, v[32:33]
	v_lshl_add_u64 v[52:53], s[6:7], 0, v[48:49]
	v_lshl_add_u64 v[48:49], s[8:9], 0, v[48:49]
	v_or_b32_e32 v56, 0x280, v144
	v_mov_b32_e32 v57, v145
	v_lshl_add_u64 v[60:61], s[6:7], 0, v[56:57]
	v_lshl_add_u64 v[56:57], s[8:9], 0, v[56:57]
	global_load_dword v37, v[36:37], off
	s_nop 0
	global_load_dword v36, v[32:33], off
	s_nop 0
	global_load_dword v33, v[52:53], off
	global_load_dword v32, v[48:49], off
	s_nop 0
	global_load_dword v49, v[60:61], off
	global_load_dword v48, v[56:57], off
	v_or_b32_e32 v52, 0x2c0, v144
	v_mov_b32_e32 v53, v145
	v_lshl_add_u64 v[56:57], s[6:7], 0, v[52:53]
	v_lshl_add_u64 v[52:53], s[8:9], 0, v[52:53]
	global_load_dword v57, v[56:57], off
	s_nop 0
	global_load_dword v56, v[52:53], off
	v_mul_f32_e32 v52, v92, v142
	v_mul_f32_e32 v53, v92, v143
	v_mov_b32_e32 v60, v50
	v_mov_b32_e32 v61, v34
	v_mul_f32_e32 v96, v92, v140
	v_mul_f32_e32 v97, v92, v141
	v_mov_b32_e32 v98, v54
	v_mov_b32_e32 v99, v38
	v_mul_f32_e32 v100, v92, v124
	v_mul_f32_e32 v101, v92, v125
	v_mov_b32_e32 v102, v58
	v_mov_b32_e32 v103, v42
	v_mul_f32_e32 v93, v92, v121
	v_mul_f32_e32 v92, v92, v120
	v_mov_b32_e32 v104, v62
	v_mov_b32_e32 v105, v46
	v_mul_f32_e32 v52, v60, v52
	v_mul_f32_e32 v53, v61, v53
	v_mul_f32_e32 v60, v98, v96
	v_mul_f32_e32 v61, v99, v97
	v_mul_f32_e32 v96, v102, v100
	v_mul_f32_e32 v97, v103, v101
	v_mul_f32_e32 v92, v104, v92
	v_mul_f32_e32 v93, v105, v93
	s_waitcnt vmcnt(7)
	v_mov_b32_e32 v100, v37
	s_waitcnt vmcnt(6)
	v_mul_f32_e32 v98, v52, v36
	v_mul_f32_e32 v99, v53, v37
	v_mov_b32_e32 v101, v36
	s_waitcnt vmcnt(4)
	v_mul_f32_e32 v102, v60, v32
	v_mul_f32_e32 v103, v61, v33
	v_mov_b32_e32 v36, v33
	v_mov_b32_e32 v37, v32
	s_waitcnt vmcnt(2)
	v_mul_f32_e32 v104, v96, v48
	v_mul_f32_e32 v105, v97, v49
	v_mov_b32_e32 v32, v49
	v_mov_b32_e32 v33, v48
	s_waitcnt vmcnt(1)
	v_mov_b32_e32 v106, v57
	s_waitcnt vmcnt(0)
	v_mov_b32_e32 v107, v56
	v_mul_f32_e32 v106, v92, v106
	v_mul_f32_e32 v107, v93, v107
	v_mul_f32_e32 v48, v92, v56
	v_mul_f32_e32 v49, v93, v57
	v_mul_f32_e32 v52, v52, v100
	v_mul_f32_e32 v53, v53, v101
	v_mul_f32_e32 v56, v60, v36
	v_mul_f32_e32 v57, v61, v37
	v_mul_f32_e32 v60, v96, v32
	v_mul_f32_e32 v61, v97, v33
	v_or_b32_e32 v32, 0x300, v144
	v_mov_b32_e32 v33, v145
	v_or_b32_e32 v92, 0x340, v144
	v_mov_b32_e32 v93, v145
	v_lshl_add_u64 v[36:37], s[6:7], 0, v[32:33]
	v_lshl_add_u64 v[96:97], s[6:7], 0, v[92:93]
	v_lshl_add_u64 v[92:93], s[8:9], 0, v[92:93]
	v_or_b32_e32 v100, 0x380, v144
	v_mov_b32_e32 v101, v145
	v_lshl_add_u64 v[32:33], s[8:9], 0, v[32:33]
	v_lshl_add_u64 v[112:113], s[6:7], 0, v[100:101]
	v_lshl_add_u64 v[100:101], s[8:9], 0, v[100:101]
	global_load_dword v114, v[36:37], off
	global_load_dword v115, v[32:33], off
	s_nop 0
	global_load_dword v96, v[96:97], off
	s_nop 0
	global_load_dword v97, v[92:93], off
	s_nop 0
	global_load_dword v92, v[112:113], off
	global_load_dword v93, v[100:101], off
	v_or_b32_e32 v32, 0x3c0, v144
	v_mov_b32_e32 v33, v145
	v_lshl_add_u64 v[36:37], s[6:7], 0, v[32:33]
	v_lshl_add_u64 v[32:33], s[8:9], 0, v[32:33]
	global_load_dword v112, v[36:37], off
	global_load_dword v113, v[32:33], off
	v_mov_b32_e32 v32, v143
	v_mov_b32_e32 v33, v142
	v_mov_b32_e32 v50, v35
	v_mov_b32_e32 v34, v141
	v_mov_b32_e32 v35, v140
	v_mov_b32_e32 v54, v39
	v_mov_b32_e32 v36, v125
	v_mov_b32_e32 v37, v124
	v_mov_b32_e32 v38, v121
	v_mov_b32_e32 v39, v120
	v_mul_f32_e32 v116, v88, v32
	v_mul_f32_e32 v117, v88, v33
	v_mov_b32_e32 v58, v43
	v_mov_b32_e32 v62, v47
	v_mul_f32_e32 v118, v88, v34
	v_mul_f32_e32 v119, v88, v35
	v_mul_f32_e32 v122, v88, v36
	v_mul_f32_e32 v123, v88, v37
	v_mul_f32_e32 v89, v88, v39
	v_mul_f32_e32 v88, v88, v38
	v_mul_f32_e32 v50, v50, v116
	v_mul_f32_e32 v51, v51, v117
	v_mul_f32_e32 v54, v54, v118
	v_mul_f32_e32 v55, v55, v119
	v_mul_f32_e32 v58, v58, v122
	v_mul_f32_e32 v59, v59, v123
	v_mul_f32_e32 v62, v62, v88
	v_mul_f32_e32 v63, v63, v89
	v_mov_b32_e32 v42, v52
	v_mov_b32_e32 v100, v60
	v_mov_b32_e32 v46, v56
	s_waitcnt vmcnt(7)
	v_mov_b32_e32 v117, v114
	s_waitcnt vmcnt(6)
	v_mov_b32_e32 v116, v115
	v_mul_f32_e32 v88, v50, v114
	v_mul_f32_e32 v89, v51, v115
	v_mul_f32_e32 v50, v50, v116
	v_mul_f32_e32 v51, v51, v117
	s_waitcnt vmcnt(3)
	v_mov_b32_e32 v123, v92
	s_waitcnt vmcnt(2)
	v_mov_b32_e32 v122, v93
	v_mul_f32_e32 v114, v54, v96
	v_mul_f32_e32 v115, v55, v97
	v_mov_b32_e32 v118, v97
	v_mov_b32_e32 v119, v96
	v_mul_f32_e32 v96, v58, v92
	v_mul_f32_e32 v97, v59, v93
	v_mul_f32_e32 v58, v58, v122
	v_mul_f32_e32 v59, v59, v123
	v_mov_b32_e32 v43, v51
	v_pk_mov_b32 v[50:51], v[52:53], v[50:51] op_sel:[1,0]
	v_mul_f32_e32 v54, v54, v118
	v_mul_f32_e32 v55, v55, v119
	v_mov_b32_e32 v101, v59
	v_pk_mov_b32 v[58:59], v[60:61], v[58:59] op_sel:[1,0]
	v_add_f32_e32 v42, v42, v50
	v_add_f32_e32 v43, v43, v51
	v_mov_b32_e32 v47, v55
	v_pk_mov_b32 v[54:55], v[56:57], v[54:55] op_sel:[1,0]
	v_add_f32_e32 v50, v100, v58
	v_add_f32_e32 v51, v101, v59
	v_mul_f32_e32 v100, v64, v42
	v_mul_f32_e32 v101, v64, v43
	s_waitcnt vmcnt(0)
	v_mov_b32_e32 v42, v113
	v_mov_b32_e32 v43, v112
	v_mul_f32_e32 v92, v62, v112
	v_mul_f32_e32 v93, v63, v113
	v_pk_mov_b32 v[126:127], v[98:99], v[88:89] op_sel:[1,0]
	v_mov_b32_e32 v99, v89
	v_pk_mov_b32 v[88:89], v[102:103], v[114:115] op_sel:[1,0]
	v_mov_b32_e32 v103, v115
	v_add_f32_e32 v46, v46, v54
	v_add_f32_e32 v47, v47, v55
	v_mul_f32_e32 v42, v62, v42
	v_mul_f32_e32 v43, v63, v43
	v_pk_mov_b32 v[114:115], v[104:105], v[96:97] op_sel:[1,0]
	v_mov_b32_e32 v105, v97
	v_pk_mov_b32 v[96:97], v[48:49], v[92:93] op_sel:[1,0]
	v_mov_b32_e32 v49, v93
	v_add_f32_e64 v52, v88, -v102
	v_add_f32_e64 v53, v89, -v103
	v_mul_f32_e32 v102, v64, v46
	v_mul_f32_e32 v103, v64, v47
	v_mov_b32_e32 v46, v106
	v_mov_b32_e32 v47, v43
	v_pk_mov_b32 v[42:43], v[106:107], v[42:43] op_sel:[1,0]
	v_add_f32_e64 v92, v126, -v98
	v_add_f32_e64 v93, v127, -v99
	v_add_f32_e64 v56, v114, -v104
	v_add_f32_e64 v57, v115, -v105
	v_add_f32_e64 v48, v96, -v48
	v_add_f32_e64 v49, v97, -v49
	v_add_f32_e32 v42, v46, v42
	v_add_f32_e32 v43, v47, v43
	v_mul_f32_e32 v88, v64, v92
	v_mul_f32_e32 v89, v64, v93
	v_mul_f32_e32 v92, v64, v52
	v_mul_f32_e32 v93, v64, v53
	v_mul_f32_e32 v96, v64, v56
	v_mul_f32_e32 v97, v64, v57
	v_mul_f32_e32 v104, v64, v50
	v_mul_f32_e32 v105, v64, v51
	v_mul_f32_e32 v98, v64, v48
	v_mul_f32_e32 v99, v64, v49
	v_mul_f32_e32 v106, v64, v42
	v_mul_f32_e32 v107, v64, v43
	v_or_b32_e32 v42, 0x1000, v144
	v_mov_b32_e32 v43, v145
	v_or_b32_e32 v48, 0x1040, v144
	v_mov_b32_e32 v49, v145
	v_lshl_add_u64 v[46:47], s[6:7], 0, v[42:43]
	v_lshl_add_u64 v[42:43], s[8:9], 0, v[42:43]
	v_lshl_add_u64 v[50:51], s[6:7], 0, v[48:49]
	v_lshl_add_u64 v[48:49], s[8:9], 0, v[48:49]
	v_or_b32_e32 v52, 0x1080, v144
	v_mov_b32_e32 v53, v145
	v_lshl_add_u64 v[54:55], s[6:7], 0, v[52:53]
	v_lshl_add_u64 v[52:53], s[8:9], 0, v[52:53]
	global_load_dword v47, v[46:47], off
	s_nop 0
	global_load_dword v46, v[42:43], off
	s_nop 0
	global_load_dword v43, v[50:51], off
	global_load_dword v42, v[48:49], off
	s_nop 0
	global_load_dword v49, v[54:55], off
	global_load_dword v48, v[52:53], off
	v_or_b32_e32 v50, 0x10c0, v144
	v_mov_b32_e32 v51, v145
	v_lshl_add_u64 v[52:53], s[6:7], 0, v[50:51]
	v_lshl_add_u64 v[50:51], s[8:9], 0, v[50:51]
	global_load_dword v53, v[52:53], off
	s_nop 0
	global_load_dword v52, v[50:51], off
	v_mul_f32_e32 v50, v108, v142
	v_mul_f32_e32 v51, v108, v143
	v_mov_b32_e32 v1, v4
	v_mul_f32_e32 v54, v108, v140
	v_mul_f32_e32 v55, v108, v141
	v_mov_b32_e32 v9, v12
	v_mul_f32_e32 v56, v108, v124
	v_mul_f32_e32 v57, v108, v125
	v_mov_b32_e32 v25, v16
	v_mul_f32_e32 v58, v108, v120
	v_mul_f32_e32 v59, v108, v121
	v_mov_b32_e32 v29, v20
	v_mul_f32_e32 v0, v0, v50
	v_mul_f32_e32 v1, v1, v51
	v_mul_f32_e32 v8, v8, v54
	v_mul_f32_e32 v9, v9, v55
	v_mul_f32_e32 v24, v24, v56
	v_mul_f32_e32 v25, v25, v57
	v_mul_f32_e32 v28, v28, v58
	v_mul_f32_e32 v29, v29, v59
	s_waitcnt vmcnt(7)
	v_mov_b32_e32 v54, v47
	s_waitcnt vmcnt(6)
	v_mov_b32_e32 v55, v46
	s_waitcnt vmcnt(5)
	v_mov_b32_e32 v56, v43
	s_waitcnt vmcnt(4)
	v_mov_b32_e32 v57, v42
	s_waitcnt vmcnt(3)
	v_mov_b32_e32 v58, v49
	s_waitcnt vmcnt(2)
	v_mov_b32_e32 v59, v48
	v_mul_f32_e32 v50, v0, v46
	v_mul_f32_e32 v51, v1, v47
	v_mul_f32_e32 v46, v8, v42
	v_mul_f32_e32 v47, v9, v43
	v_mul_f32_e32 v42, v24, v48
	v_mul_f32_e32 v43, v25, v49
	s_waitcnt vmcnt(1)
	v_mov_b32_e32 v60, v53
	s_waitcnt vmcnt(0)
	v_mov_b32_e32 v61, v52
	v_mul_f32_e32 v48, v28, v52
	v_mul_f32_e32 v49, v29, v53
	v_mul_f32_e32 v0, v0, v54
	v_mul_f32_e32 v1, v1, v55
	v_mul_f32_e32 v8, v8, v56
	v_mul_f32_e32 v9, v9, v57
	v_mul_f32_e32 v24, v24, v58
	v_mul_f32_e32 v25, v25, v59
	v_mul_f32_e32 v28, v28, v60
	v_mul_f32_e32 v29, v29, v61
	v_or_b32_e32 v52, 0x1100, v144
	v_mov_b32_e32 v53, v145
	v_lshl_add_u64 v[54:55], s[6:7], 0, v[52:53]
	v_lshl_add_u64 v[52:53], s[8:9], 0, v[52:53]
	global_load_dword v60, v[54:55], off
	global_load_dword v61, v[52:53], off
	v_or_b32_e32 v52, 0x1140, v144
	v_mov_b32_e32 v53, v145
	v_or_b32_e32 v56, 0x1180, v144
	v_mov_b32_e32 v57, v145
	v_lshl_add_u64 v[54:55], s[6:7], 0, v[52:53]
	v_lshl_add_u64 v[52:53], s[8:9], 0, v[52:53]
	v_lshl_add_u64 v[58:59], s[6:7], 0, v[56:57]
	v_lshl_add_u64 v[56:57], s[8:9], 0, v[56:57]
	global_load_dword v62, v[54:55], off
	global_load_dword v63, v[52:53], off
	s_nop 0
	global_load_dword v58, v[58:59], off
	s_nop 0
	global_load_dword v56, v[56:57], off
	v_or_b32_e32 v52, 0x11c0, v144
	v_mov_b32_e32 v53, v145
	v_lshl_add_u64 v[54:55], s[6:7], 0, v[52:53]
	v_lshl_add_u64 v[52:53], s[8:9], 0, v[52:53]
	global_load_dword v57, v[54:55], off
	global_load_dword v59, v[52:53], off
	v_mov_b32_e32 v52, v51
	v_mov_b32_e32 v40, v1
	v_mov_b32_e32 v44, v9
	v_mov_b32_e32 v4, v25
	v_mov_b32_e32 v16, v49
	v_mov_b32_e32 v20, v47
	v_mov_b32_e32 v54, v43
	v_mov_b32_e32 v12, v29
	s_waitcnt vmcnt(7)
	v_mul_f32_e32 v53, v41, v60
	s_waitcnt vmcnt(6)
	v_mul_f32_e32 v51, v21, v61
	v_mul_f32_e32 v41, v41, v61
	v_mul_f32_e32 v1, v21, v60
	v_add_f32_e32 v0, v0, v40
	v_add_f32_e32 v1, v1, v41
	s_waitcnt vmcnt(5)
	v_mul_f32_e32 v21, v45, v62
	s_waitcnt vmcnt(4)
	v_mul_f32_e32 v45, v45, v63
	v_mul_f32_e32 v9, v109, v62
	s_waitcnt vmcnt(3)
	v_mul_f32_e32 v55, v5, v58
	s_waitcnt vmcnt(2)
	v_mul_f32_e32 v49, v17, v56
	v_mul_f32_e32 v5, v5, v56
	v_mul_f32_e32 v25, v17, v58
	v_mul_f32_e32 v47, v109, v63
	s_waitcnt vmcnt(0)
	v_mul_f32_e32 v56, v110, v59
	v_mul_f32_e32 v17, v13, v57
	v_mul_f32_e32 v13, v13, v59
	v_mul_f32_e32 v29, v110, v57
	v_add_f32_e32 v8, v8, v44
	v_add_f32_e32 v9, v9, v45
	v_mov_b32_e32 v43, v49
	v_add_f32_e32 v4, v24, v4
	v_add_f32_e32 v5, v25, v5
	v_mov_b32_e32 v49, v56
	v_add_f32_e32 v12, v28, v12
	v_add_f32_e32 v13, v29, v13
	v_add_f32_e64 v24, v52, -v50
	v_add_f32_e64 v25, v53, -v51
	v_mul_f32_e32 v116, v64, v0
	v_mul_f32_e32 v117, v64, v1
	v_add_f32_e64 v0, v20, -v46
	v_add_f32_e64 v1, v21, -v47
	v_mul_f32_e32 v118, v64, v8
	v_mul_f32_e32 v119, v64, v9
	v_add_f32_e64 v8, v54, -v42
	v_add_f32_e64 v9, v55, -v43
	v_mul_f32_e32 v122, v64, v4
	v_mul_f32_e32 v123, v64, v5
	v_add_f32_e64 v4, v16, -v48
	v_add_f32_e64 v5, v17, -v49
	v_mul_f32_e32 v108, v64, v24
	v_mul_f32_e32 v109, v64, v25
	v_mul_f32_e32 v110, v64, v0
	v_mul_f32_e32 v111, v64, v1
	v_mul_f32_e32 v112, v64, v8
	v_mul_f32_e32 v113, v64, v9
	v_mul_f32_e32 v114, v64, v4
	v_mul_f32_e32 v115, v64, v5
	v_mul_f32_e32 v126, v64, v12
	v_mul_f32_e32 v127, v64, v13
	v_or_b32_e32 v0, 0x1200, v144
	v_mov_b32_e32 v1, v145
	v_or_b32_e32 v8, 0x1240, v144
	v_mov_b32_e32 v9, v145
	v_lshl_add_u64 v[4:5], s[6:7], 0, v[0:1]
	v_lshl_add_u64 v[0:1], s[8:9], 0, v[0:1]
	v_lshl_add_u64 v[12:13], s[6:7], 0, v[8:9]
	v_lshl_add_u64 v[8:9], s[8:9], 0, v[8:9]
	v_or_b32_e32 v16, 0x1280, v144
	v_mov_b32_e32 v17, v145
	v_lshl_add_u64 v[20:21], s[6:7], 0, v[16:17]
	v_lshl_add_u64 v[16:17], s[8:9], 0, v[16:17]
	global_load_dword v5, v[4:5], off
	s_nop 0
	global_load_dword v4, v[0:1], off
	s_nop 0
	global_load_dword v1, v[12:13], off
	global_load_dword v0, v[8:9], off
	s_nop 0
	global_load_dword v9, v[20:21], off
	global_load_dword v8, v[16:17], off
	v_or_b32_e32 v12, 0x12c0, v144
	v_mov_b32_e32 v13, v145
	v_lshl_add_u64 v[16:17], s[6:7], 0, v[12:13]
	v_lshl_add_u64 v[12:13], s[8:9], 0, v[12:13]
	global_load_dword v17, v[16:17], off
	s_nop 0
	global_load_dword v16, v[12:13], off
	v_mul_f32_e32 v12, v148, v142
	v_mul_f32_e32 v13, v148, v143
	v_mov_b32_e32 v20, v2
	v_mov_b32_e32 v21, v6
	v_mul_f32_e32 v24, v148, v140
	v_mul_f32_e32 v25, v148, v141
	v_mov_b32_e32 v28, v10
	v_mov_b32_e32 v29, v14
	v_mul_f32_e32 v40, v148, v124
	v_mul_f32_e32 v41, v148, v125
	v_mov_b32_e32 v42, v26
	v_mov_b32_e32 v43, v18
	v_mul_f32_e32 v44, v148, v120
	v_mul_f32_e32 v45, v148, v121
	v_mov_b32_e32 v46, v30
	v_mov_b32_e32 v47, v22
	v_mul_f32_e32 v12, v20, v12
	v_mul_f32_e32 v13, v21, v13
	v_mul_f32_e32 v20, v28, v24
	v_mul_f32_e32 v21, v29, v25
	v_mul_f32_e32 v24, v42, v40
	v_mul_f32_e32 v25, v43, v41
	v_mul_f32_e32 v28, v46, v44
	v_mul_f32_e32 v29, v47, v45
	s_waitcnt vmcnt(7)
	v_mov_b32_e32 v42, v5
	s_waitcnt vmcnt(6)
	v_mov_b32_e32 v43, v4
	s_waitcnt vmcnt(5)
	v_mov_b32_e32 v44, v1
	s_waitcnt vmcnt(4)
	v_mov_b32_e32 v45, v0
	s_waitcnt vmcnt(3)
	v_mov_b32_e32 v46, v9
	s_waitcnt vmcnt(2)
	v_mov_b32_e32 v47, v8
	v_mul_f32_e32 v40, v12, v4
	v_mul_f32_e32 v41, v13, v5
	v_mul_f32_e32 v4, v20, v0
	v_mul_f32_e32 v5, v21, v1
	v_mul_f32_e32 v0, v24, v8
	v_mul_f32_e32 v1, v25, v9
	s_waitcnt vmcnt(1)
	v_mov_b32_e32 v48, v17
	s_waitcnt vmcnt(0)
	v_mov_b32_e32 v49, v16
	v_mul_f32_e32 v8, v28, v16
	v_mul_f32_e32 v9, v29, v17
	v_mul_f32_e32 v12, v12, v42
	v_mul_f32_e32 v13, v13, v43
	v_mul_f32_e32 v16, v20, v44
	v_mul_f32_e32 v17, v21, v45
	v_mul_f32_e32 v20, v24, v46
	v_mul_f32_e32 v21, v25, v47
	v_mul_f32_e32 v24, v28, v48
	v_mul_f32_e32 v25, v29, v49
	v_or_b32_e32 v28, 0x1300, v144
	v_mov_b32_e32 v29, v145
	v_or_b32_e32 v44, 0x1340, v144
	v_mov_b32_e32 v45, v145
	v_lshl_add_u64 v[42:43], s[6:7], 0, v[28:29]
	v_lshl_add_u64 v[28:29], s[8:9], 0, v[28:29]
	v_lshl_add_u64 v[46:47], s[6:7], 0, v[44:45]
	v_lshl_add_u64 v[44:45], s[8:9], 0, v[44:45]
	v_or_b32_e32 v48, 0x1380, v144
	v_mov_b32_e32 v49, v145
	v_or_b32_e32 v144, 0x13c0, v144
	v_lshl_add_u64 v[50:51], s[6:7], 0, v[48:49]
	v_lshl_add_u64 v[48:49], s[8:9], 0, v[48:49]
	global_load_dword v42, v[42:43], off
	s_nop 0
	global_load_dword v43, v[28:29], off
	s_nop 0
	global_load_dword v28, v[46:47], off
	global_load_dword v29, v[44:45], off
	s_nop 0
	global_load_dword v44, v[50:51], off
	global_load_dword v45, v[48:49], off
	v_lshl_add_u64 v[46:47], s[6:7], 0, v[144:145]
	v_lshl_add_u64 v[48:49], s[8:9], 0, v[144:145]
	global_load_dword v46, v[46:47], off
	s_nop 0
	global_load_dword v47, v[48:49], off
	v_mul_f32_e32 v32, v32, v146
	v_mul_f32_e32 v33, v33, v146
	v_mov_b32_e32 v2, v7
	v_mul_f32_e32 v34, v34, v146
	v_mul_f32_e32 v35, v35, v146
	v_mov_b32_e32 v10, v15
	v_mul_f32_e32 v36, v36, v146
	v_mul_f32_e32 v37, v37, v146
	v_mov_b32_e32 v26, v19
	v_mul_f32_e32 v38, v38, v146
	v_mul_f32_e32 v39, v39, v146
	v_mov_b32_e32 v30, v23
	v_mul_f32_e32 v2, v2, v32
	v_mul_f32_e32 v3, v3, v33
	v_mul_f32_e32 v10, v10, v34
	v_mul_f32_e32 v11, v11, v35
	v_mul_f32_e32 v26, v26, v36
	v_mul_f32_e32 v27, v27, v37
	v_mul_f32_e32 v30, v30, v38
	v_mul_f32_e32 v31, v31, v39
	v_mov_b32_e32 v6, v12
	v_mov_b32_e32 v14, v16
	v_mov_b32_e32 v18, v20
	v_mov_b32_e32 v22, v24
	s_waitcnt vmcnt(7)
	v_mov_b32_e32 v35, v42
	s_waitcnt vmcnt(6)
	v_mul_f32_e32 v32, v2, v42
	v_mul_f32_e32 v33, v3, v43
	v_mov_b32_e32 v34, v43
	s_waitcnt vmcnt(4)
	v_mul_f32_e32 v36, v10, v28
	v_mul_f32_e32 v37, v11, v29
	v_mov_b32_e32 v38, v29
	v_mov_b32_e32 v39, v28
	s_waitcnt vmcnt(2)
	v_mul_f32_e32 v28, v26, v44
	v_mul_f32_e32 v29, v27, v45
	v_mov_b32_e32 v42, v45
	v_mov_b32_e32 v43, v44
	s_waitcnt vmcnt(0)
	v_mov_b32_e32 v48, v47
	v_mov_b32_e32 v49, v46
	v_mul_f32_e32 v44, v30, v46
	v_mul_f32_e32 v45, v31, v47
	v_pk_mov_b32 v[46:47], v[40:41], v[32:33] op_sel:[1,0]
	v_mov_b32_e32 v41, v33
	v_mul_f32_e32 v2, v2, v34
	v_mul_f32_e32 v3, v3, v35
	v_pk_mov_b32 v[32:33], v[4:5], v[36:37] op_sel:[1,0]
	v_mov_b32_e32 v5, v37
	v_mul_f32_e32 v10, v10, v38
	v_mul_f32_e32 v11, v11, v39
	v_pk_mov_b32 v[34:35], v[0:1], v[28:29] op_sel:[1,0]
	v_mov_b32_e32 v1, v29
	v_mul_f32_e32 v26, v26, v42
	v_mul_f32_e32 v27, v27, v43
	v_mul_f32_e32 v30, v30, v48
	v_mul_f32_e32 v31, v31, v49
	v_pk_mov_b32 v[28:29], v[8:9], v[44:45] op_sel:[1,0]
	v_mov_b32_e32 v9, v45
	v_mov_b32_e32 v7, v3
	v_pk_mov_b32 v[2:3], v[12:13], v[2:3] op_sel:[1,0]
	v_add_f32_e64 v4, v32, -v4
	v_add_f32_e64 v5, v33, -v5
	v_mov_b32_e32 v15, v11
	v_pk_mov_b32 v[10:11], v[16:17], v[10:11] op_sel:[1,0]
	v_add_f32_e64 v0, v34, -v0
	v_add_f32_e64 v1, v35, -v1
	v_mov_b32_e32 v19, v27
	v_pk_mov_b32 v[12:13], v[20:21], v[26:27] op_sel:[1,0]
	v_mov_b32_e32 v23, v31
	v_pk_mov_b32 v[16:17], v[24:25], v[30:31] op_sel:[1,0]
	v_add_f32_e64 v36, v46, -v40
	v_add_f32_e64 v37, v47, -v41
	v_add_f32_e64 v8, v28, -v8
	v_add_f32_e64 v9, v29, -v9
	v_add_f32_e32 v2, v6, v2
	v_add_f32_e32 v3, v7, v3
	v_mul_f32_e32 v124, v64, v4
	v_mul_f32_e32 v125, v64, v5
	v_add_f32_e32 v4, v14, v10
	v_add_f32_e32 v5, v15, v11
	v_mul_f32_e32 v140, v64, v0
	v_mul_f32_e32 v141, v64, v1
	v_add_f32_e32 v0, v18, v12
	v_add_f32_e32 v1, v19, v13
	v_add_f32_e32 v6, v22, v16
	v_add_f32_e32 v7, v23, v17
	v_mul_f32_e32 v120, v64, v36
	v_mul_f32_e32 v121, v64, v37
	v_mul_f32_e32 v142, v64, v8
	v_mul_f32_e32 v143, v64, v9
	v_mul_f32_e32 v144, v64, v2
	v_mul_f32_e32 v145, v64, v3
	v_mul_f32_e32 v146, v64, v4
	v_mul_f32_e32 v147, v64, v5
	v_mul_f32_e32 v148, v64, v0
	v_mul_f32_e32 v149, v64, v1
	v_mul_f32_e32 v150, v64, v6
	v_mul_f32_e32 v151, v64, v7
	s_and_b64 s[0:1], s[56:57], exec
	s_cselect_b32 s0, s61, 0xba00000
	s_add_u32 s4, s50, s0
	s_addc_u32 s5, s51, 0
	s_lshl_b64 s[0:1], s[54:55], 1
	s_add_u32 s0, s4, s0
	s_addc_u32 s1, s5, s1
	s_lshl_b32 s4, s33, 8
	s_add_u32 s56, s0, s4
	s_addc_u32 s57, s1, 0
	s_cbranch_execnz .LBB0_441

.LBB0_629:
	s_lshl_b32 s38, s31, 7
	v_lshl_add_u64 v[94:95], v[92:93], 0, s[38:39]
	v_readfirstlane_b32 s38, v165
	s_mov_b32 m0, s38
	s_mov_b64 s[54:55], 0x40000
	v_readfirstlane_b32 s38, v166
	global_load_lds_dwordx4 v[94:95], off
	v_lshl_add_u64 v[96:97], v[94:95], 0, s[54:55]
	s_mov_b32 m0, s38
	s_mov_b64 s[54:55], 0x80000
	v_readfirstlane_b32 s38, v167
	global_load_lds_dwordx4 v[96:97], off
	v_lshl_add_u64 v[96:97], v[94:95], 0, s[54:55]
	s_mov_b32 m0, s38
	s_mov_b64 s[54:55], 0xc0000
	v_readfirstlane_b32 s38, v168
	global_load_lds_dwordx4 v[96:97], off
	v_lshl_add_u64 v[94:95], v[94:95], 0, s[54:55]
	s_mov_b32 m0, s38
	s_lshl_b32 s31, s31, 14
	global_load_lds_dwordx4 v[94:95], off
	v_or_b32_e32 v87, s31, v106
	v_add_u32_e32 v87, v87, v109
	s_waitcnt vmcnt(0)
	s_waitcnt vmcnt(0) lgkmcnt(0)
	s_barrier
	ds_read_b128 v[94:97], v87 offset:32768
	ds_read_b128 v[102:105], v170 offset:16384
	ds_read_b128 v[180:183], v170 offset:18432
	ds_read_b128 v[184:187], v170 offset:20480
	ds_read_b128 v[98:101], v87 offset:34816
	ds_read_b128 v[188:191], v170 offset:22528
	ds_read_b128 v[192:195], v170 offset:24576
	ds_read_b128 v[196:199], v170 offset:26624
	ds_read_b128 v[200:203], v170 offset:28672
	ds_read_b128 v[204:207], v170 offset:30720
	v_or_b32_e32 v87, s31, v107
	v_add_u32_e32 v87, v87, v109
	s_waitcnt lgkmcnt(8)
	v_mfma_f32_16x16x32_bf16 v[32:35], v[94:97], v[102:105], v[32:35]
	s_mov_b32 s31, 1
	s_and_b64 vcc, exec, s[52:53]
	s_mov_b64 s[52:53], 0
	s_waitcnt lgkmcnt(7)
	v_mfma_f32_16x16x32_bf16 v[36:39], v[94:97], v[180:183], v[36:39]
	s_waitcnt lgkmcnt(6)
	v_mfma_f32_16x16x32_bf16 v[40:43], v[94:97], v[184:187], v[40:43]
	s_waitcnt lgkmcnt(4)
	v_mfma_f32_16x16x32_bf16 v[44:47], v[94:97], v[188:191], v[44:47]
	s_waitcnt lgkmcnt(3)
	v_mfma_f32_16x16x32_bf16 v[48:51], v[94:97], v[192:195], v[48:51]
	s_waitcnt lgkmcnt(2)
	v_mfma_f32_16x16x32_bf16 v[52:55], v[94:97], v[196:199], v[52:55]
	s_waitcnt lgkmcnt(1)
	v_mfma_f32_16x16x32_bf16 v[56:59], v[94:97], v[200:203], v[56:59]
	s_waitcnt lgkmcnt(0)
	v_mfma_f32_16x16x32_bf16 v[60:63], v[94:97], v[204:207], v[60:63]
	ds_read_b128 v[94:97], v87 offset:32768
	v_mfma_f32_16x16x32_bf16 v[0:3], v[98:101], v[102:105], v[0:3]
	v_mfma_f32_16x16x32_bf16 v[8:11], v[98:101], v[180:183], v[8:11]
	v_mfma_f32_16x16x32_bf16 v[12:15], v[98:101], v[184:187], v[12:15]
	v_mfma_f32_16x16x32_bf16 v[16:19], v[98:101], v[188:191], v[16:19]
	v_mfma_f32_16x16x32_bf16 v[20:23], v[98:101], v[192:195], v[20:23]
	v_mfma_f32_16x16x32_bf16 v[24:27], v[98:101], v[196:199], v[24:27]
	v_mfma_f32_16x16x32_bf16 v[28:31], v[98:101], v[200:203], v[28:31]
	v_mfma_f32_16x16x32_bf16 v[4:7], v[98:101], v[204:207], v[4:7]
	ds_read_b128 v[98:101], v87 offset:34816
	ds_read_b128 v[102:105], v172 offset:16384
	ds_read_b128 v[180:183], v172 offset:18432
	ds_read_b128 v[184:187], v172 offset:20480
	ds_read_b128 v[188:191], v172 offset:22528
	ds_read_b128 v[192:195], v172 offset:24576
	ds_read_b128 v[196:199], v172 offset:26624
	ds_read_b128 v[200:203], v172 offset:28672
	ds_read_b128 v[204:207], v172 offset:30720
	s_waitcnt lgkmcnt(7)
	v_mfma_f32_16x16x32_bf16 v[32:35], v[94:97], v[102:105], v[32:35]
	s_waitcnt lgkmcnt(0)
	s_barrier
	v_mfma_f32_16x16x32_bf16 v[36:39], v[94:97], v[180:183], v[36:39]
	v_mfma_f32_16x16x32_bf16 v[40:43], v[94:97], v[184:187], v[40:43]
	v_mfma_f32_16x16x32_bf16 v[44:47], v[94:97], v[188:191], v[44:47]
	v_mfma_f32_16x16x32_bf16 v[48:51], v[94:97], v[192:195], v[48:51]
	v_mfma_f32_16x16x32_bf16 v[52:55], v[94:97], v[196:199], v[52:55]
	v_mfma_f32_16x16x32_bf16 v[56:59], v[94:97], v[200:203], v[56:59]
	v_mfma_f32_16x16x32_bf16 v[60:63], v[94:97], v[204:207], v[60:63]
	v_mfma_f32_16x16x32_bf16 v[0:3], v[98:101], v[102:105], v[0:3]
	v_mfma_f32_16x16x32_bf16 v[8:11], v[98:101], v[180:183], v[8:11]
	v_mfma_f32_16x16x32_bf16 v[12:15], v[98:101], v[184:187], v[12:15]
	v_mfma_f32_16x16x32_bf16 v[16:19], v[98:101], v[188:191], v[16:19]
	v_mfma_f32_16x16x32_bf16 v[20:23], v[98:101], v[192:195], v[20:23]
	v_mfma_f32_16x16x32_bf16 v[24:27], v[98:101], v[196:199], v[24:27]
	v_mfma_f32_16x16x32_bf16 v[28:31], v[98:101], v[200:203], v[28:31]
	v_mfma_f32_16x16x32_bf16 v[4:7], v[98:101], v[204:207], v[4:7]
	s_cbranch_vccnz .LBB0_629
	v_and_b32_e32 v91, 64, v155
	v_xor_b32_e32 v87, 1, v155
	v_add_u32_e32 v92, 64, v91
	v_cmp_lt_i32_e32 vcc, v87, v92
	v_mov_b32_e32 v96, v56
	v_mov_b32_e32 v97, v60
	v_cndmask_b32_e32 v87, v155, v87, vcc
	v_lshlrev_b32_e32 v176, 2, v87
	v_xor_b32_e32 v87, 2, v155
	v_cmp_lt_i32_e32 vcc, v87, v92
	v_mov_b32_e32 v93, v44
	v_pk_mul_f32 v[98:99], v[96:97], v[96:97]
	v_cndmask_b32_e32 v87, v155, v87, vcc
	v_lshlrev_b32_e32 v175, 2, v87
	v_xor_b32_e32 v87, 4, v155
	v_cmp_lt_i32_e32 vcc, v87, v92
	v_mov_b32_e32 v96, v41
	v_mov_b32_e32 v97, v45
	v_cndmask_b32_e32 v87, v155, v87, vcc
	v_lshlrev_b32_e32 v91, 2, v87
	v_xor_b32_e32 v87, 8, v155
	v_cmp_lt_i32_e32 vcc, v87, v92
	v_mov_b32_e32 v92, v40
	v_pk_mul_f32 v[92:93], v[92:93], v[92:93]
	v_pk_mul_f32 v[100:101], v[96:97], v[96:97]
	v_pk_mul_f32 v[96:97], v[38:39], v[38:39]
	v_pk_mul_f32 v[102:103], v[36:37], v[36:37]
	v_mov_b32_e32 v94, v48
	v_mov_b32_e32 v95, v52
	v_pk_fma_f32 v[180:181], v[34:35], v[34:35], v[96:97]
	v_pk_fma_f32 v[102:103], v[32:33], v[32:33], v[102:103]
	v_mov_b32_e32 v96, v49
	v_mov_b32_e32 v97, v53
	v_mov_b32_e32 v210, v100
	v_mov_b32_e32 v211, v92
	v_pk_mul_f32 v[94:95], v[94:95], v[94:95]
	v_pk_mul_f32 v[182:183], v[96:97], v[96:97]
	v_pk_add_f32 v[102:103], v[102:103], v[210:211] op_sel:[1,0] op_sel_hi:[0,1]
	v_mov_b32_e32 v92, v101
	v_mov_b32_e32 v96, v57
	v_mov_b32_e32 v97, v61
	v_pk_add_f32 v[92:93], v[102:103], v[92:93]
	v_mov_b32_e32 v100, v182
	v_mov_b32_e32 v101, v94
	v_pk_mul_f32 v[184:185], v[96:97], v[96:97]
	v_pk_add_f32 v[92:93], v[92:93], v[100:101]
	v_mov_b32_e32 v94, v183
	v_pk_add_f32 v[92:93], v[92:93], v[94:95]
	v_mov_b32_e32 v94, v184
	v_mov_b32_e32 v95, v98
	v_pk_add_f32 v[92:93], v[92:93], v[94:95]
	v_mov_b32_e32 v98, v185
	v_pk_add_f32 v[92:93], v[92:93], v[98:99]
	s_nop 1
	v_mov_b32_dpp v95, v93 quad_perm:[1,0,3,2] row_mask:0xf bank_mask:0xf
	v_mov_b32_dpp v94, v92 quad_perm:[1,0,3,2] row_mask:0xf bank_mask:0xf
	v_mov_b32_e32 v96, v42
	v_mov_b32_e32 v97, v46
	v_pk_mul_f32 v[186:187], v[96:97], v[96:97]
	v_mov_b32_e32 v96, v50
	s_waitcnt lgkmcnt(0)
	v_pk_add_f32 v[92:93], v[92:93], v[94:95]
	s_nop 1
	v_mov_b32_dpp v95, v93 quad_perm:[2,3,0,1] row_mask:0xf bank_mask:0xf
	v_mov_b32_dpp v94, v92 quad_perm:[2,3,0,1] row_mask:0xf bank_mask:0xf
	v_mov_b32_e32 v97, v54
	v_pk_mul_f32 v[188:189], v[96:97], v[96:97]
	v_mov_b32_e32 v96, v58
	v_mov_b32_e32 v97, v62
	s_waitcnt lgkmcnt(0)
	v_pk_add_f32 v[92:93], v[92:93], v[94:95]
	s_nop 1
	v_mov_b32_dpp v185, v93 row_half_mirror row_mask:0xf bank_mask:0xf
	v_mov_b32_dpp v184, v92 row_half_mirror row_mask:0xf bank_mask:0xf
	v_pk_mul_f32 v[190:191], v[96:97], v[96:97]
	v_mov_b32_e32 v96, v43
	v_mov_b32_e32 v97, v47
	v_cndmask_b32_e32 v87, v155, v87, vcc
	v_pk_mul_f32 v[192:193], v[96:97], v[96:97]
	v_lshlrev_b32_e32 v87, 2, v87
	v_mov_b32_e32 v96, v51
	v_mov_b32_e32 v97, v55
	s_waitcnt lgkmcnt(0)
	v_pk_add_f32 v[92:93], v[92:93], v[184:185]
	v_mov_b32_e32 v212, v192
	v_mov_b32_e32 v213, v186
	v_pk_mul_f32 v[194:195], v[96:97], v[96:97]
	v_mov_b32_e32 v98, v14
	v_mov_b32_e32 v99, v18
	v_mov_b32_dpp v185, v93 row_mirror row_mask:0xf bank_mask:0xf
	v_mov_b32_dpp v184, v92 row_mirror row_mask:0xf bank_mask:0xf
	v_pk_add_f32 v[180:181], v[180:181], v[212:213] op_sel:[1,0] op_sel_hi:[0,1]
	v_mov_b32_e32 v186, v193
	v_mov_b32_e32 v96, v59
	v_mov_b32_e32 v97, v63
	v_pk_mul_f32 v[102:103], v[98:99], v[98:99]
	v_mov_b32_e32 v98, v22
	v_mov_b32_e32 v99, v26
	v_pk_add_f32 v[180:181], v[180:181], v[186:187]
	v_mov_b32_e32 v186, v194
	v_mov_b32_e32 v187, v188
	v_pk_mul_f32 v[196:197], v[96:97], v[96:97]
	v_pk_mul_f32 v[100:101], v[98:99], v[98:99]
	v_mov_b32_e32 v98, v30
	v_mov_b32_e32 v99, v6
	v_pk_add_f32 v[180:181], v[180:181], v[186:187]
	v_mov_b32_e32 v188, v195
	v_mov_b32_e32 v208, v29
	v_mov_b32_e32 v209, v5
	v_pk_mul_f32 v[94:95], v[98:99], v[98:99]
	v_mov_b32_e32 v98, v15
	v_mov_b32_e32 v99, v19
	v_pk_add_f32 v[180:181], v[180:181], v[188:189]
	v_mov_b32_e32 v186, v196
	v_mov_b32_e32 v187, v190
	v_pk_mul_f32 v[182:183], v[208:209], v[208:209]
	v_pk_mul_f32 v[208:209], v[98:99], v[98:99]
	v_mov_b32_e32 v98, v23
	v_mov_b32_e32 v99, v27
	s_mov_b32 s38, 0x358637bd
	v_pk_add_f32 v[180:181], v[180:181], v[186:187]
	v_mov_b32_e32 v190, v197
	v_pk_mul_f32 v[210:211], v[98:99], v[98:99]
	s_waitcnt lgkmcnt(0)
	v_pk_add_f32 v[98:99], v[92:93], v[184:185]
	v_mov_b64_e32 v[92:93], s[38:39]
	v_pk_add_f32 v[180:181], v[180:181], v[190:191]
	v_pk_fma_f32 v[184:185], v[98:99], s[46:47], v[92:93] op_sel_hi:[1,0,0]
	s_nop 0
	v_mov_b32_dpp v187, v181 quad_perm:[1,0,3,2] row_mask:0xf bank_mask:0xf
	v_mov_b32_dpp v186, v180 quad_perm:[1,0,3,2] row_mask:0xf bank_mask:0xf
	v_mul_f32_e32 v98, 0x4b800000, v185
	v_cmp_gt_f32_e32 vcc, s58, v185
	v_mov_b32_e32 v96, v12
	v_mov_b32_e32 v97, v16
	v_cndmask_b32_e32 v98, v185, v98, vcc
	v_rsq_f32_e32 v177, v98
	s_waitcnt lgkmcnt(0)
	v_pk_add_f32 v[180:181], v[180:181], v[186:187]
	s_nop 1
	v_mov_b32_dpp v187, v181 quad_perm:[2,3,0,1] row_mask:0xf bank_mask:0xf
	v_mov_b32_dpp v186, v180 quad_perm:[2,3,0,1] row_mask:0xf bank_mask:0xf
	v_mul_f32_e32 v185, 0x45800000, v177
	v_cndmask_b32_e32 v177, v177, v185, vcc
	v_mul_f32_e32 v214, v32, v177
	v_mul_f32_e32 v32, 0x4b800000, v184
	v_cmp_gt_f32_e32 vcc, s58, v184
	s_waitcnt lgkmcnt(0)
	v_pk_add_f32 v[180:181], v[180:181], v[186:187]
	s_nop 1
	v_mov_b32_dpp v185, v181 row_half_mirror row_mask:0xf bank_mask:0xf
	v_cndmask_b32_e32 v32, v184, v32, vcc
	v_rsq_f32_e32 v32, v32
	v_mov_b32_dpp v184, v180 row_half_mirror row_mask:0xf bank_mask:0xf
	v_mul_f32_e32 v215, v36, v177
	v_mul_f32_e32 v216, v40, v177
	v_mul_f32_e32 v36, 0x45800000, v32
	v_cndmask_b32_e32 v36, v32, v36, vcc
	v_mul_f32_e32 v44, v44, v177
	v_mul_f32_e32 v48, v48, v177
	v_mul_f32_e32 v52, v52, v177
	v_mul_f32_e32 v56, v56, v177
	v_mul_f32_e32 v60, v60, v177
	v_mul_f32_e32 v177, v33, v36
	s_waitcnt lgkmcnt(0)
	v_pk_add_f32 v[32:33], v[180:181], v[184:185]
	s_nop 1
	v_mov_b32_dpp v181, v33 row_mirror row_mask:0xf bank_mask:0xf
	v_mov_b32_dpp v180, v32 row_mirror row_mask:0xf bank_mask:0xf
	v_mul_f32_e32 v184, v37, v36
	v_pk_mul_f32 v[198:199], v[96:97], v[96:97]
	v_mov_b32_e32 v96, v20
	v_mov_b32_e32 v97, v24
	s_waitcnt lgkmcnt(0)
	v_pk_add_f32 v[32:33], v[32:33], v[180:181]
	v_pk_mul_f32 v[200:201], v[96:97], v[96:97]
	v_pk_fma_f32 v[32:33], v[32:33], s[46:47], v[92:93] op_sel_hi:[1,0,0]
	v_mov_b32_e32 v96, v28
	v_mul_f32_e32 v37, 0x4b800000, v33
	v_cmp_gt_f32_e32 vcc, s58, v33
	v_mov_b32_e32 v97, v4
	v_pk_mul_f32 v[104:105], v[96:97], v[96:97]
	v_cndmask_b32_e32 v33, v33, v37, vcc
	v_rsq_f32_e32 v33, v33
	v_mov_b32_e32 v96, v13
	v_mov_b32_e32 v97, v17
	v_pk_mul_f32 v[202:203], v[96:97], v[96:97]
	v_pk_mul_f32 v[204:205], v[8:9], v[8:9]
	v_mul_f32_e32 v185, v41, v36
	v_mul_f32_e32 v45, v45, v36
	v_mul_f32_e32 v49, v49, v36
	v_mul_f32_e32 v53, v53, v36
	v_mul_f32_e32 v57, v57, v36
	v_mul_f32_e32 v61, v61, v36
	v_mul_f32_e32 v36, 0x45800000, v33
	v_pk_fma_f32 v[204:205], v[0:1], v[0:1], v[204:205]
	v_mov_b32_e32 v206, v21
	v_mov_b32_e32 v207, v25
	v_cndmask_b32_e32 v180, v33, v36, vcc
	v_mov_b32_e32 v36, v202
	v_mov_b32_e32 v37, v198
	v_pk_mul_f32 v[206:207], v[206:207], v[206:207]
	v_pk_add_f32 v[36:37], v[204:205], v[36:37] op_sel:[1,0] op_sel_hi:[0,1]
	v_mov_b32_e32 v198, v203
	v_pk_add_f32 v[36:37], v[36:37], v[198:199]
	v_mov_b32_e32 v40, v206
	v_mov_b32_e32 v41, v200
	v_pk_add_f32 v[36:37], v[36:37], v[40:41]
	v_mov_b32_e32 v200, v207
	v_pk_add_f32 v[36:37], v[36:37], v[200:201]
	v_mov_b32_e32 v40, v182
	v_mov_b32_e32 v41, v104
	v_pk_add_f32 v[36:37], v[36:37], v[40:41]
	v_mov_b32_e32 v104, v183
	v_pk_add_f32 v[36:37], v[36:37], v[104:105]
	s_nop 1
	v_mov_b32_dpp v41, v37 quad_perm:[1,0,3,2] row_mask:0xf bank_mask:0xf
	v_mov_b32_dpp v40, v36 quad_perm:[1,0,3,2] row_mask:0xf bank_mask:0xf
	v_mul_f32_e32 v33, 0x4b800000, v32
	v_cmp_gt_f32_e32 vcc, s58, v32
	v_mul_f32_e32 v181, v34, v180
	v_mul_f32_e32 v186, v42, v180
	s_waitcnt lgkmcnt(0)
	v_pk_add_f32 v[36:37], v[36:37], v[40:41]
	s_nop 1
	v_mov_b32_dpp v41, v37 quad_perm:[2,3,0,1] row_mask:0xf bank_mask:0xf
	v_mov_b32_dpp v40, v36 quad_perm:[2,3,0,1] row_mask:0xf bank_mask:0xf
	v_cndmask_b32_e32 v32, v32, v33, vcc
	v_rsq_f32_e32 v34, v32
	v_pk_mul_f32 v[96:97], v[10:11], v[10:11]
	v_mul_f32_e32 v38, v38, v180
	s_waitcnt lgkmcnt(0)
	v_pk_add_f32 v[32:33], v[36:37], v[40:41]
	s_nop 1
	v_mov_b32_dpp v37, v33 row_half_mirror row_mask:0xf bank_mask:0xf
	v_mov_b32_dpp v36, v32 row_half_mirror row_mask:0xf bank_mask:0xf
	v_mul_f32_e32 v40, 0x45800000, v34
	v_cndmask_b32_e32 v42, v34, v40, vcc
	v_mul_f32_e32 v104, v35, v42
	v_pk_fma_f32 v[96:97], v[2:3], v[2:3], v[96:97]
	s_waitcnt lgkmcnt(0)
	v_pk_add_f32 v[32:33], v[32:33], v[36:37]
	s_nop 1
	v_mov_b32_dpp v35, v33 row_mirror row_mask:0xf bank_mask:0xf
	v_mov_b32_dpp v34, v32 row_mirror row_mask:0xf bank_mask:0xf
	v_mov_b32_e32 v36, v210
	v_mov_b32_e32 v37, v100
	v_mov_b32_e32 v100, v211
	v_mul_f32_e32 v39, v39, v42
	s_waitcnt lgkmcnt(0)
	v_pk_add_f32 v[32:33], v[32:33], v[34:35]
	v_mul_f32_e32 v105, v43, v42
	v_pk_fma_f32 v[40:41], v[32:33], s[46:47], v[92:93] op_sel_hi:[1,0,0]
	v_mul_f32_e32 v47, v47, v42
	v_mul_f32_e32 v32, 0x4b800000, v41
	v_cmp_gt_f32_e32 vcc, s58, v41
	v_mul_f32_e32 v51, v51, v42
	v_mul_f32_e32 v35, v55, v42
	v_cndmask_b32_e32 v32, v41, v32, vcc
	v_rsq_f32_e32 v32, v32
	v_mul_f32_e32 v41, v59, v42
	v_mul_f32_e32 v55, v63, v42
	v_add_u32_e32 v63, 0x400, v150
	v_mul_f32_e32 v33, 0x45800000, v32
	v_cndmask_b32_e32 v59, v32, v33, vcc
	v_mov_b32_e32 v32, v208
	v_mov_b32_e32 v33, v102
	v_pk_add_f32 v[32:33], v[96:97], v[32:33] op_sel:[1,0] op_sel_hi:[0,1]
	v_mov_b32_e32 v102, v209
	v_pk_add_f32 v[32:33], v[32:33], v[102:103]
	s_lshl_b32 s38, s59, 1
	v_pk_add_f32 v[32:33], v[32:33], v[36:37]
	v_mul_f32_e32 v46, v46, v180
	v_pk_add_f32 v[42:43], v[32:33], v[100:101]
	v_lshl_add_u64 v[32:33], s[34:35], 0, v[68:69]
	v_lshlrev_b64 v[32:33], 12, v[32:33]
	v_lshl_add_u64 v[32:33], s[36:37], 0, v[32:33]
	v_mul_f32_e32 v50, v50, v180
	v_mul_f32_e32 v54, v54, v180
	v_mul_f32_e32 v58, v58, v180
	v_mul_f32_e32 v62, v62, v180
	ds_write2_b32 v150, v214, v215 offset1:16
	ds_write2_b32 v150, v177, v184 offset0:128 offset1:144
	ds_write2_b32 v63, v181, v38 offset1:16
	ds_write2_b32 v63, v104, v39 offset0:128 offset1:144
	ds_write2_b32 v150, v216, v44 offset0:32 offset1:48
	ds_write2_b32 v150, v185, v45 offset0:160 offset1:176
	ds_write2_b32 v63, v186, v46 offset0:32 offset1:48
	ds_write2_b32 v63, v105, v47 offset0:160 offset1:176
	ds_write2_b32 v150, v48, v52 offset0:64 offset1:80
	ds_write2_b32 v150, v49, v53 offset0:192 offset1:208
	ds_write2_b32 v63, v50, v54 offset0:64 offset1:80
	ds_write2_b32 v63, v51, v35 offset0:192 offset1:208
	ds_write2st64_b32 v151, v56, v57 offset1:2
	ds_write2st64_b32 v151, v58, v41 offset0:4 offset1:6
	ds_write2st64_b32 v154, v60, v61 offset1:2
	ds_write2st64_b32 v154, v62, v55 offset0:4 offset1:6
	v_lshl_add_u64 v[32:33], v[32:33], 0, s[38:39]
	v_lshl_add_u64 v[32:33], v[32:33], 0, v[64:65]
	global_load_dwordx4 v[36:39], v[32:33], off offset:2048
	v_mov_b32_e32 v98, v31
	v_mov_b32_e32 v99, v7
	v_pk_mul_f32 v[98:99], v[98:99], v[98:99]
	v_mov_b32_e32 v45, v94
	v_mov_b32_e32 v44, v98
	v_pk_add_f32 v[42:43], v[42:43], v[44:45]
	v_mov_b32_e32 v94, v99
	v_pk_add_f32 v[42:43], v[42:43], v[94:95]
	s_nop 1
	v_mov_b32_dpp v45, v43 quad_perm:[1,0,3,2] row_mask:0xf bank_mask:0xf
	v_mov_b32_dpp v44, v42 quad_perm:[1,0,3,2] row_mask:0xf bank_mask:0xf
	v_mul_f32_e32 v34, v0, v59
	v_mul_f32_e32 v0, v12, v59
	v_mul_f32_e32 v12, 0x4b800000, v40
	v_cmp_gt_f32_e32 vcc, s58, v40
	s_waitcnt lgkmcnt(0)
	v_pk_add_f32 v[42:43], v[42:43], v[44:45]
	s_nop 1
	v_mov_b32_dpp v45, v43 quad_perm:[2,3,0,1] row_mask:0xf bank_mask:0xf
	v_mov_b32_dpp v44, v42 quad_perm:[2,3,0,1] row_mask:0xf bank_mask:0xf
	v_cndmask_b32_e32 v12, v40, v12, vcc
	v_rsq_f32_e32 v12, v12
	v_mul_f32_e32 v48, v4, v59
	v_mul_f32_e32 v46, v20, v59
	s_waitcnt lgkmcnt(0)
	v_pk_add_f32 v[40:41], v[42:43], v[44:45]
	s_nop 1
	v_mov_b32_dpp v43, v41 row_half_mirror row_mask:0xf bank_mask:0xf
	v_mov_b32_dpp v42, v40 row_half_mirror row_mask:0xf bank_mask:0xf
	v_mul_f32_e32 v4, 0x45800000, v12
	v_cndmask_b32_e32 v4, v12, v4, vcc
	v_mul_f32_e32 v49, v13, v4
	v_mul_f32_e32 v35, v16, v59
	s_waitcnt lgkmcnt(0)
	v_pk_add_f32 v[40:41], v[40:41], v[42:43]
	s_nop 1
	v_mov_b32_dpp v43, v41 row_mirror row_mask:0xf bank_mask:0xf
	v_mov_b32_dpp v42, v40 row_mirror row_mask:0xf bank_mask:0xf
	v_mul_f32_e32 v50, v17, v4
	v_lshl_add_u64 v[16:17], s[34:35], 0, v[70:71]
	v_mul_f32_e32 v1, v1, v4
	v_mul_f32_e32 v9, v9, v4
	s_waitcnt lgkmcnt(0)
	v_pk_add_f32 v[12:13], v[40:41], v[42:43]
	v_mul_f32_e32 v51, v21, v4
	v_pk_fma_f32 v[12:13], v[12:13], s[46:47], v[92:93] op_sel_hi:[1,0,0]
	v_lshlrev_b64 v[16:17], 12, v[16:17]
	v_mul_f32_e32 v20, 0x4b800000, v13
	v_cmp_gt_f32_e32 vcc, s58, v13
	v_mul_f32_e32 v52, v25, v4
	v_mul_f32_e32 v29, v29, v4
	v_cndmask_b32_e32 v13, v13, v20, vcc
	v_rsq_f32_e32 v13, v13
	v_mul_f32_e32 v53, v5, v4
	v_lshl_add_u64 v[16:17], s[36:37], 0, v[16:17]
	v_lshl_add_u64 v[16:17], v[16:17], 0, s[38:39]
	v_mul_f32_e32 v4, 0x45800000, v13
	v_cndmask_b32_e32 v4, v13, v4, vcc
	v_mul_f32_e32 v54, v2, v4
	v_mul_f32_e32 v2, 0x4b800000, v12
	v_cmp_gt_f32_e32 vcc, s58, v12
	v_lshl_add_u64 v[44:45], v[16:17], 0, v[64:65]
	global_load_dwordx4 v[40:43], v[44:45], off offset:2048
	v_cndmask_b32_e32 v2, v12, v2, vcc
	v_rsq_f32_e32 v2, v2
	v_mul_f32_e32 v8, v8, v59
	v_mul_f32_e32 v47, v24, v59
	v_mul_f32_e32 v28, v28, v59
	v_mul_f32_e32 v55, v10, v4
	v_mul_f32_e32 v56, v14, v4
	v_mul_f32_e32 v57, v18, v4
	v_mul_f32_e32 v58, v22, v4
	v_mul_f32_e32 v26, v26, v4
	v_mul_f32_e32 v30, v30, v4
	v_mul_f32_e32 v59, v6, v4
	v_mul_f32_e32 v4, 0x45800000, v2
	v_cndmask_b32_e32 v6, v2, v4, vcc
	v_mul_f32_e32 v60, v3, v6
	v_lshl_add_u64 v[2:3], s[34:35], 0, v[72:73]
	v_lshlrev_b64 v[2:3], 12, v[2:3]
	v_lshl_add_u64 v[2:3], s[36:37], 0, v[2:3]
	v_lshl_add_u64 v[2:3], v[2:3], 0, s[38:39]
	v_mul_f32_e32 v61, v11, v6
	v_mul_f32_e32 v91, v23, v6
	v_lshl_add_u64 v[22:23], v[2:3], 0, v[64:65]
	ds_read_b128 v[10:13], v149
	global_load_dwordx4 v[2:5], v[22:23], off offset:2048
	v_mul_f32_e32 v62, v15, v6
	v_mul_f32_e32 v87, v19, v6
	v_mul_f32_e32 v27, v27, v6
	v_mul_f32_e32 v31, v31, v6
	v_mul_f32_e32 v92, v7, v6
	s_waitcnt vmcnt(2)
	v_and_b32_e32 v7, 0xffff0000, v36
	v_lshlrev_b32_e32 v6, 16, v36
	ds_read_b128 v[14:17], v149 offset:16
	s_waitcnt lgkmcnt(1)
	v_pk_mul_f32 v[6:7], v[10:11], v[6:7]
	v_and_b32_e32 v11, 0xffff0000, v37
	v_bfe_u32 v24, v7, 16, 1
	v_bfe_u32 v25, v6, 16, 1
	v_add3_u32 v25, v6, v25, s47
	v_add3_u32 v24, v7, v24, s47
	v_lshl_add_u64 v[6:7], s[34:35], 0, v[74:75]
	v_lshlrev_b32_e32 v10, 16, v37
	v_lshlrev_b64 v[6:7], 12, v[6:7]
	v_pk_mul_f32 v[10:11], v[12:13], v[10:11]
	v_and_b32_e32 v13, 0xffff0000, v38
	v_lshlrev_b32_e32 v12, 16, v38
	v_lshl_add_u64 v[6:7], s[36:37], 0, v[6:7]
	s_waitcnt lgkmcnt(0)
	v_pk_mul_f32 v[12:13], v[14:15], v[12:13]
	v_lshl_add_u64 v[6:7], v[6:7], 0, s[38:39]
	v_bfe_u32 v18, v13, 16, 1
	v_bfe_u32 v19, v12, 16, 1
	v_bfe_u32 v20, v11, 16, 1
	v_bfe_u32 v21, v10, 16, 1
	v_lshl_add_u64 v[6:7], v[6:7], 0, v[64:65]
	v_add3_u32 v21, v10, v21, s47
	v_add3_u32 v20, v11, v20, s47
	v_add3_u32 v19, v12, v19, s47
	v_add3_u32 v18, v13, v18, s47
	global_load_dwordx4 v[10:13], v[6:7], off offset:2048
	v_and_b32_e32 v15, 0xffff0000, v39
	v_lshlrev_b32_e32 v14, 16, v39
	v_pk_mul_f32 v[14:15], v[16:17], v[14:15]
	s_add_i32 s30, s30, s3
	v_cvt_pk_bf16_f32 v17, v14, v15
	v_perm_b32 v16, v18, v19, s33
	v_perm_b32 v15, v20, v21, s33
	ds_read_b128 v[18:21], v157
	v_perm_b32 v14, v24, v25, s33
	global_store_dwordx4 v[32:33], v[14:17], off offset:2048
	ds_read_b128 v[14:17], v157 offset:16
	s_cmpk_lt_i32 s30, 0x400
	s_waitcnt vmcnt(3)
	v_and_b32_e32 v25, 0xffff0000, v40
	v_lshlrev_b32_e32 v24, 16, v40
	s_waitcnt lgkmcnt(1)
	v_pk_mul_f32 v[18:19], v[18:19], v[24:25]
	v_and_b32_e32 v25, 0xffff0000, v41
	v_lshlrev_b32_e32 v24, 16, v41
	v_pk_mul_f32 v[20:21], v[20:21], v[24:25]
	v_and_b32_e32 v25, 0xffff0000, v42
	v_lshlrev_b32_e32 v24, 16, v42
	s_waitcnt lgkmcnt(0)
	v_pk_mul_f32 v[14:15], v[14:15], v[24:25]
	v_and_b32_e32 v25, 0xffff0000, v43
	v_lshlrev_b32_e32 v24, 16, v43
	v_pk_mul_f32 v[16:17], v[16:17], v[24:25]
	v_cvt_pk_bf16_f32 v17, v16, v17
	v_cvt_pk_bf16_f32 v16, v14, v15
	v_cvt_pk_bf16_f32 v15, v20, v21
	v_cvt_pk_bf16_f32 v14, v18, v19
	ds_read_b128 v[18:21], v158
	global_store_dwordx4 v[44:45], v[14:17], off offset:2048
	ds_read_b128 v[14:17], v158 offset:16
	s_waitcnt vmcnt(3)
	v_and_b32_e32 v25, 0xffff0000, v2
	v_lshlrev_b32_e32 v24, 16, v2
	s_waitcnt lgkmcnt(1)
	v_pk_mul_f32 v[18:19], v[18:19], v[24:25]
	v_and_b32_e32 v25, 0xffff0000, v3
	v_lshlrev_b32_e32 v24, 16, v3
	v_pk_mul_f32 v[2:3], v[20:21], v[24:25]
	v_and_b32_e32 v21, 0xffff0000, v4
	v_lshlrev_b32_e32 v20, 16, v4
	s_waitcnt lgkmcnt(0)
	v_pk_mul_f32 v[14:15], v[14:15], v[20:21]
	v_and_b32_e32 v21, 0xffff0000, v5
	v_lshlrev_b32_e32 v20, 16, v5
	v_pk_mul_f32 v[4:5], v[16:17], v[20:21]
	v_cvt_pk_bf16_f32 v5, v4, v5
	v_cvt_pk_bf16_f32 v4, v14, v15
	ds_read_b128 v[14:17], v159
	v_cvt_pk_bf16_f32 v3, v2, v3
	v_cvt_pk_bf16_f32 v2, v18, v19
	global_store_dwordx4 v[22:23], v[2:5], off offset:2048
	ds_read_b128 v[2:5], v159 offset:16
	s_waitcnt vmcnt(3)
	v_and_b32_e32 v19, 0xffff0000, v10
	v_lshlrev_b32_e32 v18, 16, v10
	s_waitcnt lgkmcnt(1)
	v_pk_mul_f32 v[14:15], v[14:15], v[18:19]
	v_and_b32_e32 v19, 0xffff0000, v11
	v_lshlrev_b32_e32 v18, 16, v11
	v_pk_mul_f32 v[10:11], v[16:17], v[18:19]
	v_and_b32_e32 v17, 0xffff0000, v12
	v_lshlrev_b32_e32 v16, 16, v12
	s_waitcnt lgkmcnt(0)
	v_pk_mul_f32 v[2:3], v[2:3], v[16:17]
	v_and_b32_e32 v17, 0xffff0000, v13
	v_lshlrev_b32_e32 v16, 16, v13
	v_pk_mul_f32 v[4:5], v[4:5], v[16:17]
	v_cvt_pk_bf16_f32 v5, v4, v5
	v_cvt_pk_bf16_f32 v4, v2, v3
	v_cvt_pk_bf16_f32 v3, v10, v11
	v_cvt_pk_bf16_f32 v2, v14, v15
	global_store_dwordx4 v[6:7], v[2:5], off offset:2048
	ds_write2_b32 v150, v34, v8 offset1:16
	ds_write2_b32 v150, v1, v9 offset0:128 offset1:144
	ds_write2_b32 v63, v54, v55 offset1:16
	ds_write2_b32 v63, v60, v61 offset0:128 offset1:144
	ds_write2_b32 v150, v0, v35 offset0:32 offset1:48
	ds_write2_b32 v150, v49, v50 offset0:160 offset1:176
	ds_write2_b32 v63, v56, v57 offset0:32 offset1:48
	ds_write2_b32 v63, v62, v87 offset0:160 offset1:176
	ds_write2_b32 v150, v46, v47 offset0:64 offset1:80
	ds_write2_b32 v150, v51, v52 offset0:192 offset1:208
	ds_write2_b32 v63, v58, v26 offset0:64 offset1:80
	ds_write2_b32 v63, v91, v27 offset0:192 offset1:208
	ds_write2st64_b32 v151, v28, v29 offset1:2
	ds_write2st64_b32 v151, v30, v31 offset0:4 offset1:6
	ds_write2st64_b32 v154, v48, v53 offset1:2
	ds_write2st64_b32 v154, v59, v92 offset0:4 offset1:6
	v_lshl_add_u64 v[0:1], s[34:35], 0, v[76:77]
	v_lshlrev_b64 v[0:1], 12, v[0:1]
	v_lshl_add_u64 v[0:1], s[36:37], 0, v[0:1]
	v_lshl_add_u64 v[0:1], v[0:1], 0, s[38:39]
	v_lshl_add_u64 v[20:21], v[0:1], 0, v[64:65]
	global_load_dwordx4 v[0:3], v[20:21], off offset:2048
	v_lshl_add_u64 v[4:5], s[34:35], 0, v[78:79]
	v_lshlrev_b64 v[4:5], 12, v[4:5]
	v_lshl_add_u64 v[4:5], s[36:37], 0, v[4:5]
	v_lshl_add_u64 v[4:5], v[4:5], 0, s[38:39]
	v_lshl_add_u64 v[22:23], v[4:5], 0, v[64:65]
	global_load_dwordx4 v[4:7], v[22:23], off offset:2048
	v_lshl_add_u64 v[8:9], s[34:35], 0, v[80:81]
	v_lshlrev_b64 v[8:9], 12, v[8:9]
	v_lshl_add_u64 v[8:9], s[36:37], 0, v[8:9]
	v_lshl_add_u64 v[8:9], v[8:9], 0, s[38:39]
	v_lshl_add_u64 v[24:25], v[8:9], 0, v[64:65]
	global_load_dwordx4 v[8:11], v[24:25], off offset:2048
	ds_read_b128 v[12:15], v149
	ds_read_b128 v[16:19], v149 offset:16
	s_waitcnt vmcnt(2)
	v_and_b32_e32 v27, 0xffff0000, v0
	v_lshlrev_b32_e32 v26, 16, v0
	s_waitcnt lgkmcnt(1)
	v_pk_mul_f32 v[12:13], v[12:13], v[26:27]
	v_and_b32_e32 v27, 0xffff0000, v1
	v_lshlrev_b32_e32 v26, 16, v1
	v_pk_mul_f32 v[0:1], v[14:15], v[26:27]
	v_bfe_u32 v28, v13, 16, 1
	v_bfe_u32 v26, v1, 16, 1
	v_bfe_u32 v27, v0, 16, 1
	v_bfe_u32 v29, v12, 16, 1
	v_add3_u32 v12, v12, v29, s47
	v_add3_u32 v28, v13, v28, s47
	v_add3_u32 v13, v0, v27, s47
	v_add3_u32 v29, v1, v26, s47
	v_lshl_add_u64 v[0:1], s[34:35], 0, v[82:83]
	v_lshlrev_b64 v[0:1], 12, v[0:1]
	v_and_b32_e32 v15, 0xffff0000, v2
	v_lshlrev_b32_e32 v14, 16, v2
	v_lshl_add_u64 v[0:1], s[36:37], 0, v[0:1]
	s_waitcnt lgkmcnt(0)
	v_pk_mul_f32 v[14:15], v[16:17], v[14:15]
	v_lshl_add_u64 v[0:1], v[0:1], 0, s[38:39]
	v_and_b32_e32 v17, 0xffff0000, v3
	v_lshlrev_b32_e32 v16, 16, v3
	v_lshl_add_u64 v[26:27], v[0:1], 0, v[64:65]
	global_load_dwordx4 v[0:3], v[26:27], off offset:2048
	v_pk_mul_f32 v[16:17], v[18:19], v[16:17]
	v_cvt_pk_bf16_f32 v14, v14, v15
	v_bfe_u32 v18, v17, 16, 1
	v_bfe_u32 v19, v16, 16, 1
	v_add3_u32 v15, v16, v19, s47
	v_add3_u32 v16, v17, v18, s47
	v_perm_b32 v15, v16, v15, s33
	ds_read_b128 v[16:19], v157
	v_perm_b32 v13, v29, v13, s33
	v_perm_b32 v12, v28, v12, s33
	global_store_dwordx4 v[20:21], v[12:15], off offset:2048
	ds_read_b128 v[12:15], v157 offset:16
	s_waitcnt vmcnt(3)
	v_and_b32_e32 v21, 0xffff0000, v4
	v_lshlrev_b32_e32 v20, 16, v4
	s_waitcnt lgkmcnt(1)
	v_pk_mul_f32 v[16:17], v[16:17], v[20:21]
	v_and_b32_e32 v21, 0xffff0000, v5
	v_lshlrev_b32_e32 v20, 16, v5
	v_pk_mul_f32 v[4:5], v[18:19], v[20:21]
	v_and_b32_e32 v19, 0xffff0000, v6
	v_lshlrev_b32_e32 v18, 16, v6
	s_waitcnt lgkmcnt(0)
	v_pk_mul_f32 v[12:13], v[12:13], v[18:19]
	v_and_b32_e32 v19, 0xffff0000, v7
	v_lshlrev_b32_e32 v18, 16, v7
	v_pk_mul_f32 v[6:7], v[14:15], v[18:19]
	v_cvt_pk_bf16_f32 v7, v6, v7
	v_cvt_pk_bf16_f32 v6, v12, v13
	ds_read_b128 v[12:15], v158
	v_cvt_pk_bf16_f32 v5, v4, v5
	v_cvt_pk_bf16_f32 v4, v16, v17
	global_store_dwordx4 v[22:23], v[4:7], off offset:2048
	ds_read_b128 v[4:7], v158 offset:16
	s_waitcnt vmcnt(3)
	v_and_b32_e32 v17, 0xffff0000, v8
	v_lshlrev_b32_e32 v16, 16, v8
	s_waitcnt lgkmcnt(1)
	v_pk_mul_f32 v[12:13], v[12:13], v[16:17]
	v_and_b32_e32 v17, 0xffff0000, v9
	v_lshlrev_b32_e32 v16, 16, v9
	v_pk_mul_f32 v[8:9], v[14:15], v[16:17]
	v_and_b32_e32 v15, 0xffff0000, v10
	v_lshlrev_b32_e32 v14, 16, v10
	s_waitcnt lgkmcnt(0)
	v_pk_mul_f32 v[4:5], v[4:5], v[14:15]
	v_and_b32_e32 v15, 0xffff0000, v11
	v_lshlrev_b32_e32 v14, 16, v11
	v_pk_mul_f32 v[6:7], v[6:7], v[14:15]
	v_cvt_pk_bf16_f32 v7, v6, v7
	v_cvt_pk_bf16_f32 v6, v4, v5
	v_cvt_pk_bf16_f32 v5, v8, v9
	ds_read_b128 v[8:11], v159
	v_cvt_pk_bf16_f32 v4, v12, v13
	global_store_dwordx4 v[24:25], v[4:7], off offset:2048
	ds_read_b128 v[4:7], v159 offset:16
	s_waitcnt vmcnt(3)
	v_and_b32_e32 v13, 0xffff0000, v0
	v_lshlrev_b32_e32 v12, 16, v0
	s_waitcnt lgkmcnt(1)
	v_pk_mul_f32 v[8:9], v[8:9], v[12:13]
	v_and_b32_e32 v13, 0xffff0000, v1
	v_lshlrev_b32_e32 v12, 16, v1
	v_pk_mul_f32 v[0:1], v[10:11], v[12:13]
	v_and_b32_e32 v11, 0xffff0000, v2
	v_lshlrev_b32_e32 v10, 16, v2
	s_waitcnt lgkmcnt(0)
	v_pk_mul_f32 v[4:5], v[4:5], v[10:11]
	v_and_b32_e32 v11, 0xffff0000, v3
	v_lshlrev_b32_e32 v10, 16, v3
	v_pk_mul_f32 v[2:3], v[6:7], v[10:11]
	v_cvt_pk_bf16_f32 v3, v2, v3
	v_cvt_pk_bf16_f32 v2, v4, v5
	v_cvt_pk_bf16_f32 v1, v0, v1
	v_cvt_pk_bf16_f32 v0, v8, v9
	global_store_dwordx4 v[26:27], v[0:3], off offset:2048
	s_cbranch_scc1 .LBB0_624
	v_readlane_b32 s96, v247, 7
	v_readlane_b32 s54, v247, 5
	v_readlane_b32 s97, v247, 8
	v_readlane_b32 s55, v247, 6
